# FFN_IN swiglu epilogue: hoist 8 ssq loads, drop per-group vmcnt(0)
# speedup vs baseline: 1.0056x; 1.0056x over previous
.LBB0_152:
	ds_read_b128 v[160:163], v155
	ds_read_b128 v[164:167], v155 offset:1024
	ds_read_b128 v[168:171], v155 offset:2048
	ds_read_b128 v[172:175], v155 offset:3072
	ds_read_b128 v[176:179], v156
	ds_read_b128 v[180:183], v156 offset:1024
	ds_read_b128 v[184:187], v156 offset:2048
	ds_read_b128 v[188:191], v156 offset:3072
	s_add_u32 s50, s48, 0xfffc0080
	s_addc_u32 s51, s49, -1
	s_cmp_eq_u32 s73, 12
	s_cselect_b32 s53, s27, s51
	s_cselect_b32 s52, s69, s50
	s_cselect_b32 s51, s25, s72
	s_cselect_b32 s50, s70, s71
	v_lshl_add_u64 v[148:149], s[48:49], 0, v[140:141]
	s_add_i32 m0, s57, 0xc000
	ds_read_b128 v[192:195], v157
	ds_read_b128 v[196:199], v157 offset:1024
	ds_read_b128 v[200:203], v157 offset:2048
	ds_read_b128 v[204:207], v157 offset:3072
	ds_read_b128 v[208:211], v157 offset:4096
	ds_read_b128 v[212:215], v157 offset:5120
	ds_read_b128 v[216:219], v157 offset:6144
	ds_read_b128 v[220:223], v157 offset:7168
	global_load_lds_dwordx4 v[148:149], off
	v_lshl_add_u64 v[148:149], s[48:49], 0, v[142:143]
	s_add_i32 m0, s57, 0xe000
	s_nop 0
	global_load_lds_dwordx4 v[148:149], off
	s_waitcnt vmcnt(8)
	s_waitcnt lgkmcnt(0)
	s_barrier
	s_setprio 1
	s_waitcnt lgkmcnt(0)
	v_mfma_f32_16x16x32_bf16 v[118:121], v[160:163], v[192:195], v[118:121]
	v_mfma_f32_16x16x32_bf16 v[114:117], v[168:171], v[192:195], v[114:117]
	v_mfma_f32_16x16x32_bf16 v[106:109], v[160:163], v[200:203], v[106:109]
	v_mfma_f32_16x16x32_bf16 v[98:101], v[168:171], v[200:203], v[98:101]
	v_mfma_f32_16x16x32_bf16 v[90:93], v[160:163], v[208:211], v[90:93]
	v_mfma_f32_16x16x32_bf16 v[82:85], v[168:171], v[208:211], v[82:85]
	v_mfma_f32_16x16x32_bf16 v[74:77], v[160:163], v[216:219], v[74:77]
	v_mfma_f32_16x16x32_bf16 v[66:69], v[168:171], v[216:219], v[66:69]
	v_mfma_f32_16x16x32_bf16 v[118:121], v[164:167], v[196:199], v[118:121]
	v_mfma_f32_16x16x32_bf16 v[114:117], v[172:175], v[196:199], v[114:117]
	v_mfma_f32_16x16x32_bf16 v[106:109], v[164:167], v[204:207], v[106:109]
	v_mfma_f32_16x16x32_bf16 v[98:101], v[172:175], v[204:207], v[98:101]
	v_mfma_f32_16x16x32_bf16 v[90:93], v[164:167], v[212:215], v[90:93]
	v_mfma_f32_16x16x32_bf16 v[82:85], v[172:175], v[212:215], v[82:85]
	v_mfma_f32_16x16x32_bf16 v[74:77], v[164:167], v[220:223], v[74:77]
	v_mfma_f32_16x16x32_bf16 v[66:69], v[172:175], v[220:223], v[66:69]
	s_setprio 0
	s_setprio 1
	v_mfma_f32_16x16x32_bf16 v[126:129], v[176:179], v[192:195], v[126:129]
	v_mfma_f32_16x16x32_bf16 v[122:125], v[184:187], v[192:195], v[122:125]
	v_mfma_f32_16x16x32_bf16 v[110:113], v[176:179], v[200:203], v[110:113]
	v_mfma_f32_16x16x32_bf16 v[102:105], v[184:187], v[200:203], v[102:105]
	v_mfma_f32_16x16x32_bf16 v[94:97], v[176:179], v[208:211], v[94:97]
	v_mfma_f32_16x16x32_bf16 v[86:89], v[184:187], v[208:211], v[86:89]
	v_mfma_f32_16x16x32_bf16 v[78:81], v[176:179], v[216:219], v[78:81]
	v_mfma_f32_16x16x32_bf16 v[70:73], v[184:187], v[216:219], v[70:73]
	v_mfma_f32_16x16x32_bf16 v[126:129], v[180:183], v[196:199], v[126:129]
	v_mfma_f32_16x16x32_bf16 v[122:125], v[188:191], v[196:199], v[122:125]
	v_mfma_f32_16x16x32_bf16 v[110:113], v[180:183], v[204:207], v[110:113]
	v_mfma_f32_16x16x32_bf16 v[102:105], v[188:191], v[204:207], v[102:105]
	v_mfma_f32_16x16x32_bf16 v[94:97], v[180:183], v[212:215], v[94:97]
	v_mfma_f32_16x16x32_bf16 v[86:89], v[188:191], v[212:215], v[86:89]
	v_mfma_f32_16x16x32_bf16 v[78:81], v[180:183], v[220:223], v[78:81]
	v_mfma_f32_16x16x32_bf16 v[70:73], v[188:191], v[220:223], v[70:73]
	s_setprio 0
	s_barrier
	s_add_i32 s74, s66, s54
	v_lshl_add_u64 v[148:149], s[50:51], 0, v[134:135]
	s_mov_b32 m0, s74
	ds_read_b128 v[192:195], v157 offset:16384
	ds_read_b128 v[196:199], v157 offset:17408
	ds_read_b128 v[200:203], v157 offset:18432
	ds_read_b128 v[204:207], v157 offset:19456
	ds_read_b128 v[208:211], v157 offset:20480
	ds_read_b128 v[212:215], v157 offset:21504
	ds_read_b128 v[216:219], v157 offset:22528
	ds_read_b128 v[220:223], v157 offset:23552
	global_load_lds_dwordx4 v[148:149], off
	s_add_i32 m0, s74, 0x2000
	s_add_u32 s74, s50, 0x40000
	v_lshl_add_u64 v[224:225], s[50:51], 0, v[130:131]
	s_addc_u32 s75, s51, 0
	s_add_i32 s76, s67, s54
	global_load_lds_dwordx4 v[224:225], off
	v_lshl_add_u64 v[226:227], s[74:75], 0, v[134:135]
	s_mov_b32 m0, s76
	v_lshl_add_u64 v[228:229], s[52:53], 0, v[132:133]
	global_load_lds_dwordx4 v[226:227], off
	v_lshl_add_u64 v[226:227], s[74:75], 0, v[130:131]
	s_add_i32 m0, s76, 0x2000
	s_nop 0
	global_load_lds_dwordx4 v[226:227], off
	v_lshl_add_u64 v[226:227], s[52:53], 0, v[136:137]
	s_mov_b32 m0, s57
	s_nop 0
	global_load_lds_dwordx4 v[226:227], off
	s_mov_b32 m0, s58
	s_nop 0
	global_load_lds_dwordx4 v[228:229], off
	s_waitcnt vmcnt(8)
	s_waitcnt lgkmcnt(0)
	s_barrier
	s_setprio 1
	s_waitcnt lgkmcnt(0)
	v_mfma_f32_16x16x32_bf16 v[58:61], v[160:163], v[192:195], v[58:61]
	v_mfma_f32_16x16x32_bf16 v[50:53], v[168:171], v[192:195], v[50:53]
	v_mfma_f32_16x16x32_bf16 v[42:45], v[160:163], v[200:203], v[42:45]
	v_mfma_f32_16x16x32_bf16 v[34:37], v[168:171], v[200:203], v[34:37]
	v_mfma_f32_16x16x32_bf16 v[26:29], v[160:163], v[208:211], v[26:29]
	v_mfma_f32_16x16x32_bf16 v[18:21], v[168:171], v[208:211], v[18:21]
	v_mfma_f32_16x16x32_bf16 v[10:13], v[160:163], v[216:219], v[10:13]
	v_mfma_f32_16x16x32_bf16 v[6:9], v[168:171], v[216:219], v[6:9]
	v_mfma_f32_16x16x32_bf16 v[58:61], v[164:167], v[196:199], v[58:61]
	v_mfma_f32_16x16x32_bf16 v[50:53], v[172:175], v[196:199], v[50:53]
	v_mfma_f32_16x16x32_bf16 v[42:45], v[164:167], v[204:207], v[42:45]
	v_mfma_f32_16x16x32_bf16 v[34:37], v[172:175], v[204:207], v[34:37]
	v_mfma_f32_16x16x32_bf16 v[26:29], v[164:167], v[212:215], v[26:29]
	v_mfma_f32_16x16x32_bf16 v[18:21], v[172:175], v[212:215], v[18:21]
	v_mfma_f32_16x16x32_bf16 v[10:13], v[164:167], v[220:223], v[10:13]
	v_mfma_f32_16x16x32_bf16 v[6:9], v[172:175], v[220:223], v[6:9]
	s_setprio 0
	s_setprio 1
	v_mfma_f32_16x16x32_bf16 v[62:65], v[176:179], v[192:195], v[62:65]
	v_mfma_f32_16x16x32_bf16 v[54:57], v[184:187], v[192:195], v[54:57]
	v_mfma_f32_16x16x32_bf16 v[46:49], v[176:179], v[200:203], v[46:49]
	v_mfma_f32_16x16x32_bf16 v[38:41], v[184:187], v[200:203], v[38:41]
	v_mfma_f32_16x16x32_bf16 v[30:33], v[176:179], v[208:211], v[30:33]
	v_mfma_f32_16x16x32_bf16 v[22:25], v[184:187], v[208:211], v[22:25]
	v_mfma_f32_16x16x32_bf16 v[14:17], v[176:179], v[216:219], v[14:17]
	v_mfma_f32_16x16x32_bf16 v[2:5], v[184:187], v[216:219], v[2:5]
	v_mfma_f32_16x16x32_bf16 v[62:65], v[180:183], v[196:199], v[62:65]
	v_mfma_f32_16x16x32_bf16 v[54:57], v[188:191], v[196:199], v[54:57]
	v_mfma_f32_16x16x32_bf16 v[46:49], v[180:183], v[204:207], v[46:49]
	v_mfma_f32_16x16x32_bf16 v[38:41], v[188:191], v[204:207], v[38:41]
	v_mfma_f32_16x16x32_bf16 v[30:33], v[180:183], v[212:215], v[30:33]
	v_mfma_f32_16x16x32_bf16 v[22:25], v[188:191], v[212:215], v[22:25]
	v_mfma_f32_16x16x32_bf16 v[14:17], v[180:183], v[220:223], v[14:17]
	v_mfma_f32_16x16x32_bf16 v[2:5], v[188:191], v[220:223], v[2:5]
	s_setprio 0
	s_barrier
	s_add_i32 s74, 0, 0x18000
	v_add_u32_e32 v159, s74, v151
	s_add_i32 s75, 0, 0x1c000
	ds_read_b128 v[160:163], v159
	ds_read_b128 v[164:167], v159 offset:1024
	ds_read_b128 v[168:171], v159 offset:2048
	ds_read_b128 v[172:175], v159 offset:3072
	v_add_u32_e32 v159, s75, v151
	ds_read_b128 v[176:179], v159
	ds_read_b128 v[180:183], v159 offset:1024
	ds_read_b128 v[184:187], v159 offset:2048
	ds_read_b128 v[188:191], v159 offset:3072
	s_add_u32 s52, s52, 0x40000
	s_addc_u32 s53, s53, 0
	s_mov_b32 m0, s59
	v_lshl_add_u64 v[230:231], s[52:53], 0, v[136:137]
	ds_read_b128 v[192:195], v157 offset:32768
	ds_read_b128 v[196:199], v157 offset:33792
	ds_read_b128 v[200:203], v157 offset:34816
	ds_read_b128 v[204:207], v157 offset:35840
	ds_read_b128 v[208:211], v157 offset:36864
	ds_read_b128 v[212:215], v157 offset:37888
	ds_read_b128 v[216:219], v157 offset:38912
	ds_read_b128 v[220:223], v157 offset:39936
	global_load_lds_dwordx4 v[230:231], off
	v_lshl_add_u64 v[230:231], s[52:53], 0, v[132:133]
	s_mov_b32 m0, s60
	s_nop 0
	global_load_lds_dwordx4 v[230:231], off
	s_waitcnt vmcnt(8)
	s_waitcnt lgkmcnt(0)
	s_barrier
	s_setprio 1
	s_waitcnt lgkmcnt(0)
	v_mfma_f32_16x16x32_bf16 v[118:121], v[160:163], v[192:195], v[118:121]
	v_mfma_f32_16x16x32_bf16 v[114:117], v[168:171], v[192:195], v[114:117]
	v_mfma_f32_16x16x32_bf16 v[106:109], v[160:163], v[200:203], v[106:109]
	v_mfma_f32_16x16x32_bf16 v[98:101], v[168:171], v[200:203], v[98:101]
	v_mfma_f32_16x16x32_bf16 v[90:93], v[160:163], v[208:211], v[90:93]
	v_mfma_f32_16x16x32_bf16 v[82:85], v[168:171], v[208:211], v[82:85]
	v_mfma_f32_16x16x32_bf16 v[74:77], v[160:163], v[216:219], v[74:77]
	v_mfma_f32_16x16x32_bf16 v[66:69], v[168:171], v[216:219], v[66:69]
	v_mfma_f32_16x16x32_bf16 v[118:121], v[164:167], v[196:199], v[118:121]
	v_mfma_f32_16x16x32_bf16 v[114:117], v[172:175], v[196:199], v[114:117]
	v_mfma_f32_16x16x32_bf16 v[106:109], v[164:167], v[204:207], v[106:109]
	v_mfma_f32_16x16x32_bf16 v[98:101], v[172:175], v[204:207], v[98:101]
	v_mfma_f32_16x16x32_bf16 v[90:93], v[164:167], v[212:215], v[90:93]
	v_mfma_f32_16x16x32_bf16 v[82:85], v[172:175], v[212:215], v[82:85]
	v_mfma_f32_16x16x32_bf16 v[74:77], v[164:167], v[220:223], v[74:77]
	v_mfma_f32_16x16x32_bf16 v[66:69], v[172:175], v[220:223], v[66:69]
	s_setprio 0
	s_setprio 1
	v_mfma_f32_16x16x32_bf16 v[126:129], v[176:179], v[192:195], v[126:129]
	v_mfma_f32_16x16x32_bf16 v[122:125], v[184:187], v[192:195], v[122:125]
	v_mfma_f32_16x16x32_bf16 v[110:113], v[176:179], v[200:203], v[110:113]
	v_mfma_f32_16x16x32_bf16 v[102:105], v[184:187], v[200:203], v[102:105]
	v_mfma_f32_16x16x32_bf16 v[94:97], v[176:179], v[208:211], v[94:97]
	v_mfma_f32_16x16x32_bf16 v[86:89], v[184:187], v[208:211], v[86:89]
	v_mfma_f32_16x16x32_bf16 v[78:81], v[176:179], v[216:219], v[78:81]
	v_mfma_f32_16x16x32_bf16 v[70:73], v[184:187], v[216:219], v[70:73]
	v_mfma_f32_16x16x32_bf16 v[126:129], v[180:183], v[196:199], v[126:129]
	v_mfma_f32_16x16x32_bf16 v[122:125], v[188:191], v[196:199], v[122:125]
	v_mfma_f32_16x16x32_bf16 v[110:113], v[180:183], v[204:207], v[110:113]
	v_mfma_f32_16x16x32_bf16 v[102:105], v[188:191], v[204:207], v[102:105]
	v_mfma_f32_16x16x32_bf16 v[94:97], v[180:183], v[212:215], v[94:97]
	v_mfma_f32_16x16x32_bf16 v[86:89], v[188:191], v[212:215], v[86:89]
	v_mfma_f32_16x16x32_bf16 v[78:81], v[180:183], v[220:223], v[78:81]
	v_mfma_f32_16x16x32_bf16 v[70:73], v[188:191], v[220:223], v[70:73]
	s_setprio 0
	s_barrier
	s_add_i32 s52, s74, s54
	v_lshl_add_u64 v[148:149], v[148:149], 0, s[14:15]
	s_mov_b32 m0, s52
	ds_read_b128 v[192:195], v157 offset:49152
	ds_read_b128 v[196:199], v157 offset:50176
	ds_read_b128 v[200:203], v157 offset:51200
	ds_read_b128 v[204:207], v157 offset:52224
	ds_read_b128 v[208:211], v157 offset:53248
	ds_read_b128 v[212:215], v157 offset:54272
	ds_read_b128 v[216:219], v157 offset:55296
	ds_read_b128 v[220:223], v157 offset:56320
	global_load_lds_dwordx4 v[148:149], off
	s_add_i32 m0, s52, 0x2000
	s_add_u32 s50, s50, 0x40080
	v_lshl_add_u64 v[148:149], v[224:225], 0, s[14:15]
	s_addc_u32 s51, s51, 0
	s_add_i32 s52, s75, s54
	global_load_lds_dwordx4 v[148:149], off
	v_lshl_add_u64 v[148:149], s[50:51], 0, v[134:135]
	s_mov_b32 m0, s52
	s_nop 0
	global_load_lds_dwordx4 v[148:149], off
	v_lshl_add_u64 v[148:149], s[50:51], 0, v[130:131]
	s_add_i32 m0, s52, 0x2000
	s_nop 0
	global_load_lds_dwordx4 v[148:149], off
	v_lshl_add_u64 v[148:149], v[226:227], 0, s[14:15]
	s_mov_b32 m0, s62
	s_nop 0
	global_load_lds_dwordx4 v[148:149], off
	v_lshl_add_u64 v[148:149], v[228:229], 0, s[14:15]
	s_mov_b32 m0, s63
	s_nop 0
	global_load_lds_dwordx4 v[148:149], off
	s_waitcnt vmcnt(8)
	s_waitcnt lgkmcnt(0)
	s_barrier
	s_setprio 1
	s_waitcnt lgkmcnt(0)
	v_mfma_f32_16x16x32_bf16 v[58:61], v[160:163], v[192:195], v[58:61]
	v_mfma_f32_16x16x32_bf16 v[50:53], v[168:171], v[192:195], v[50:53]
	v_mfma_f32_16x16x32_bf16 v[42:45], v[160:163], v[200:203], v[42:45]
	v_mfma_f32_16x16x32_bf16 v[34:37], v[168:171], v[200:203], v[34:37]
	v_mfma_f32_16x16x32_bf16 v[26:29], v[160:163], v[208:211], v[26:29]
	v_mfma_f32_16x16x32_bf16 v[18:21], v[168:171], v[208:211], v[18:21]
	v_mfma_f32_16x16x32_bf16 v[10:13], v[160:163], v[216:219], v[10:13]
	v_mfma_f32_16x16x32_bf16 v[6:9], v[168:171], v[216:219], v[6:9]
	v_mfma_f32_16x16x32_bf16 v[58:61], v[164:167], v[196:199], v[58:61]
	v_mfma_f32_16x16x32_bf16 v[50:53], v[172:175], v[196:199], v[50:53]
	v_mfma_f32_16x16x32_bf16 v[42:45], v[164:167], v[204:207], v[42:45]
	v_mfma_f32_16x16x32_bf16 v[34:37], v[172:175], v[204:207], v[34:37]
	v_mfma_f32_16x16x32_bf16 v[26:29], v[164:167], v[212:215], v[26:29]
	v_mfma_f32_16x16x32_bf16 v[18:21], v[172:175], v[212:215], v[18:21]
	v_mfma_f32_16x16x32_bf16 v[10:13], v[164:167], v[220:223], v[10:13]
	v_mfma_f32_16x16x32_bf16 v[6:9], v[172:175], v[220:223], v[6:9]
	s_setprio 0
	s_setprio 1
	v_mfma_f32_16x16x32_bf16 v[62:65], v[176:179], v[192:195], v[62:65]
	v_mfma_f32_16x16x32_bf16 v[54:57], v[184:187], v[192:195], v[54:57]
	v_mfma_f32_16x16x32_bf16 v[46:49], v[176:179], v[200:203], v[46:49]
	v_mfma_f32_16x16x32_bf16 v[38:41], v[184:187], v[200:203], v[38:41]
	v_mfma_f32_16x16x32_bf16 v[30:33], v[176:179], v[208:211], v[30:33]
	v_mfma_f32_16x16x32_bf16 v[22:25], v[184:187], v[208:211], v[22:25]
	v_mfma_f32_16x16x32_bf16 v[14:17], v[176:179], v[216:219], v[14:17]
	v_mfma_f32_16x16x32_bf16 v[2:5], v[184:187], v[216:219], v[2:5]
	v_mfma_f32_16x16x32_bf16 v[62:65], v[180:183], v[196:199], v[62:65]
	v_mfma_f32_16x16x32_bf16 v[54:57], v[188:191], v[196:199], v[54:57]
	v_mfma_f32_16x16x32_bf16 v[46:49], v[180:183], v[204:207], v[46:49]
	v_mfma_f32_16x16x32_bf16 v[38:41], v[188:191], v[204:207], v[38:41]
	v_mfma_f32_16x16x32_bf16 v[30:33], v[180:183], v[212:215], v[30:33]
	v_mfma_f32_16x16x32_bf16 v[22:25], v[188:191], v[212:215], v[22:25]
	v_mfma_f32_16x16x32_bf16 v[14:17], v[180:183], v[220:223], v[14:17]
	v_mfma_f32_16x16x32_bf16 v[2:5], v[188:191], v[220:223], v[2:5]
	s_setprio 0
	s_barrier
	s_add_i32 s73, s73, 2
	s_add_u32 s48, s48, 0x100
	s_addc_u32 s49, s49, 0
	s_add_u32 s71, s71, 0x100
	s_addc_u32 s72, s72, 0
	s_cmp_gt_u32 s73, 13
	s_cbranch_scc0 .LBB0_152
	s_lshl_b32 s25, s46, 8
	v_add_u32_e32 v148, s25, v150
	v_ashrrev_i32_e32 v149, 31, v148
	v_lshl_add_u64 v[160:161], v[148:149], 2, s[8:9]
	global_load_dword v149, v[160:161], off
	global_load_dword v232, v[160:161], off offset:64
	global_load_dword v233, v[160:161], off offset:128
	global_load_dword v234, v[160:161], off offset:192
	global_load_dword v235, v[160:161], off offset:512
	global_load_dword v236, v[160:161], off offset:576
	global_load_dword v237, v[160:161], off offset:640
	global_load_dword v238, v[160:161], off offset:704
	s_and_b64 vcc, exec, s[16:17]
	s_cbranch_vccz .LBB0_155
	s_barrier
.LBB0_155:
	v_pk_mul_f32 v[128:129], v[120:121], v[128:129]
	v_pk_mul_f32 v[126:127], v[118:119], v[126:127]
	v_pk_mul_f32 v[124:125], v[116:117], v[124:125]
	v_pk_mul_f32 v[160:161], v[114:115], v[122:123]
	v_add_u32_e32 v162, s25, v152
	s_lshl_b32 s46, s47, 7
	v_mov_b64_e32 v[122:123], s[12:13]
	s_ashr_i32 s47, s46, 31
	v_mad_i64_i32 v[164:165], s[48:49], v148, s68, v[122:123]
	s_lshl_b64 s[46:47], s[46:47], 1
	v_lshl_add_u64 v[164:165], v[164:165], 0, s[46:47]
	v_lshl_add_u64 v[164:165], v[164:165], 0, v[138:139]
	v_pk_mul_f32 v[112:113], v[108:109], v[112:113]
	v_pk_mul_f32 v[110:111], v[106:107], v[110:111]
	v_pk_mul_f32 v[104:105], v[100:101], v[104:105]
	v_pk_mul_f32 v[102:103], v[98:99], v[102:103]
	v_pk_mul_f32 v[96:97], v[92:93], v[96:97]
	v_pk_mul_f32 v[94:95], v[90:91], v[94:95]
	v_pk_mul_f32 v[88:89], v[84:85], v[88:89]
	v_pk_mul_f32 v[86:87], v[82:83], v[86:87]
	v_pk_mul_f32 v[80:81], v[76:77], v[80:81]
	v_pk_mul_f32 v[78:79], v[74:75], v[78:79]
	v_pk_mul_f32 v[72:73], v[68:69], v[72:73]
	v_pk_mul_f32 v[70:71], v[66:67], v[70:71]
	v_pk_mul_f32 v[64:65], v[60:61], v[64:65]
	v_pk_mul_f32 v[62:63], v[58:59], v[62:63]
	v_pk_mul_f32 v[56:57], v[52:53], v[56:57]
	v_pk_mul_f32 v[54:55], v[50:51], v[54:55]
	v_pk_mul_f32 v[48:49], v[44:45], v[48:49]
	v_pk_mul_f32 v[46:47], v[42:43], v[46:47]
	v_pk_mul_f32 v[40:41], v[36:37], v[40:41]
	v_pk_mul_f32 v[38:39], v[34:35], v[38:39]
	v_pk_mul_f32 v[32:33], v[28:29], v[32:33]
	v_pk_mul_f32 v[30:31], v[26:27], v[30:31]
	v_pk_mul_f32 v[24:25], v[20:21], v[24:25]
	v_pk_mul_f32 v[22:23], v[18:19], v[22:23]
	v_pk_mul_f32 v[16:17], v[12:13], v[16:17]
	v_pk_mul_f32 v[14:15], v[10:11], v[14:15]
	v_pk_mul_f32 v[4:5], v[8:9], v[4:5]
	v_pk_mul_f32 v[2:3], v[6:7], v[2:3]
	s_andn2_b64 vcc, exec, s[4:5]
	s_waitcnt vmcnt(0)
	v_fmamk_f32 v149, v149, 0x3a800000, v158
	v_rsq_f32_e32 v149, v149
	s_nop 0
	v_mul_f32_e32 v168, 0xbfb8aa3b, v149
	v_pk_mul_f32 v[120:121], v[120:121], v[168:169] op_sel_hi:[1,0]
	v_pk_mul_f32 v[118:119], v[118:119], v[168:169] op_sel_hi:[1,0]
	v_pk_mul_f32 v[116:117], v[116:117], v[168:169] op_sel_hi:[1,0]
	v_pk_mul_f32 v[114:115], v[114:115], v[168:169] op_sel_hi:[1,0]
	v_exp_f32_e32 v118, v118
	v_exp_f32_e32 v119, v119
	v_exp_f32_e32 v120, v120
	v_exp_f32_e32 v121, v121
	v_exp_f32_e32 v114, v114
	v_exp_f32_e32 v115, v115
	v_exp_f32_e32 v116, v116
	v_exp_f32_e32 v117, v117
	v_mul_f32_e32 v170, v149, v149
	v_add_f32_e32 v118, 1.0, v118
	v_add_f32_e32 v119, 1.0, v119
	v_add_f32_e32 v120, 1.0, v120
	v_add_f32_e32 v121, 1.0, v121
	v_add_f32_e32 v149, 1.0, v114
	v_add_f32_e32 v159, 1.0, v115
	v_add_f32_e32 v163, 1.0, v116
	v_add_f32_e32 v168, 1.0, v117
	v_rcp_f32_e32 v114, v118
	v_rcp_f32_e32 v115, v119
	v_rcp_f32_e32 v116, v120
	v_rcp_f32_e32 v117, v121
	v_rcp_f32_e32 v118, v149
	v_rcp_f32_e32 v119, v159
	v_rcp_f32_e32 v120, v163
	v_rcp_f32_e32 v121, v168
	v_pk_mul_f32 v[114:115], v[170:171], v[114:115] op_sel_hi:[0,1]
	v_pk_mul_f32 v[116:117], v[170:171], v[116:117] op_sel_hi:[0,1]
	v_pk_mul_f32 v[118:119], v[170:171], v[118:119] op_sel_hi:[0,1]
	v_pk_mul_f32 v[120:121], v[170:171], v[120:121] op_sel_hi:[0,1]
	v_pk_mul_f32 v[116:117], v[128:129], v[116:117]
	v_pk_mul_f32 v[114:115], v[126:127], v[114:115]
	v_pk_mul_f32 v[120:121], v[124:125], v[120:121]
	v_pk_mul_f32 v[118:119], v[160:161], v[118:119]
	v_cvt_pk_bf16_f32 v114, v114, v115
	v_cvt_pk_bf16_f32 v115, v116, v117
	v_cvt_pk_bf16_f32 v116, v118, v119
	v_cvt_pk_bf16_f32 v117, v120, v121
	global_store_dwordx4 v[164:165], v[114:117], off
	v_fmamk_f32 v118, v232, 0x3a800000, v158
	v_rsq_f32_e32 v121, v118
	v_add_u32_e32 v114, s25, v153
	v_mul_f32_e32 v120, 0xbfb8aa3b, v121
	v_pk_mul_f32 v[108:109], v[108:109], v[120:121] op_sel_hi:[1,0]
	v_pk_mul_f32 v[106:107], v[106:107], v[120:121] op_sel_hi:[1,0]
	v_pk_mul_f32 v[100:101], v[100:101], v[120:121] op_sel_hi:[1,0]
	v_pk_mul_f32 v[98:99], v[98:99], v[120:121] op_sel_hi:[1,0]
	v_exp_f32_e32 v106, v106
	v_exp_f32_e32 v107, v107
	v_exp_f32_e32 v108, v108
	v_exp_f32_e32 v109, v109
	v_exp_f32_e32 v98, v98
	v_exp_f32_e32 v99, v99
	v_exp_f32_e32 v100, v100
	v_exp_f32_e32 v101, v101
	v_mul_f32_e32 v124, v121, v121
	v_add_f32_e32 v106, 1.0, v106
	v_add_f32_e32 v107, 1.0, v107
	v_add_f32_e32 v108, 1.0, v108
	v_add_f32_e32 v109, 1.0, v109
	v_add_f32_e32 v115, 1.0, v98
	v_add_f32_e32 v120, 1.0, v99
	v_add_f32_e32 v121, 1.0, v100
	v_add_f32_e32 v125, 1.0, v101
	v_rcp_f32_e32 v98, v106
	v_rcp_f32_e32 v99, v107
	v_rcp_f32_e32 v100, v108
	v_rcp_f32_e32 v101, v109
	v_rcp_f32_e32 v106, v115
	v_rcp_f32_e32 v107, v120
	v_rcp_f32_e32 v108, v121
	v_rcp_f32_e32 v109, v125
	v_mad_i64_i32 v[116:117], s[48:49], v162, s68, v[122:123]
	v_pk_mul_f32 v[98:99], v[124:125], v[98:99] op_sel_hi:[0,1]
	v_pk_mul_f32 v[100:101], v[124:125], v[100:101] op_sel_hi:[0,1]
	v_pk_mul_f32 v[106:107], v[124:125], v[106:107] op_sel_hi:[0,1]
	v_pk_mul_f32 v[108:109], v[124:125], v[108:109] op_sel_hi:[0,1]
	v_lshl_add_u64 v[116:117], v[116:117], 0, s[46:47]
	v_pk_mul_f32 v[100:101], v[112:113], v[100:101]
	v_pk_mul_f32 v[98:99], v[110:111], v[98:99]
	v_pk_mul_f32 v[104:105], v[104:105], v[108:109]
	v_pk_mul_f32 v[102:103], v[102:103], v[106:107]
	v_lshl_add_u64 v[116:117], v[116:117], 0, v[138:139]
	v_cvt_pk_bf16_f32 v98, v98, v99
	v_cvt_pk_bf16_f32 v99, v100, v101
	v_cvt_pk_bf16_f32 v100, v102, v103
	v_cvt_pk_bf16_f32 v101, v104, v105
	global_store_dwordx4 v[116:117], v[98:101], off
	v_fmamk_f32 v102, v233, 0x3a800000, v158
	v_rsq_f32_e32 v105, v102
	v_add_u32_e32 v98, s25, v154
	v_mul_f32_e32 v104, 0xbfb8aa3b, v105
	v_pk_mul_f32 v[92:93], v[92:93], v[104:105] op_sel_hi:[1,0]
	v_pk_mul_f32 v[90:91], v[90:91], v[104:105] op_sel_hi:[1,0]
	v_pk_mul_f32 v[84:85], v[84:85], v[104:105] op_sel_hi:[1,0]
	v_pk_mul_f32 v[82:83], v[82:83], v[104:105] op_sel_hi:[1,0]
	v_exp_f32_e32 v90, v90
	v_exp_f32_e32 v91, v91
	v_exp_f32_e32 v92, v92
	v_exp_f32_e32 v93, v93
	v_exp_f32_e32 v82, v82
	v_exp_f32_e32 v83, v83
	v_exp_f32_e32 v84, v84
	v_exp_f32_e32 v85, v85
	v_mul_f32_e32 v106, v105, v105
	v_add_f32_e32 v90, 1.0, v90
	v_add_f32_e32 v91, 1.0, v91
	v_add_f32_e32 v92, 1.0, v92
	v_add_f32_e32 v93, 1.0, v93
	v_add_f32_e32 v99, 1.0, v82
	v_add_f32_e32 v104, 1.0, v83
	v_add_f32_e32 v105, 1.0, v84
	v_add_f32_e32 v107, 1.0, v85
	v_rcp_f32_e32 v82, v90
	v_rcp_f32_e32 v83, v91
	v_rcp_f32_e32 v84, v92
	v_rcp_f32_e32 v85, v93
	v_rcp_f32_e32 v90, v99
	v_rcp_f32_e32 v91, v104
	v_rcp_f32_e32 v92, v105
	v_rcp_f32_e32 v93, v107
	v_mad_i64_i32 v[100:101], s[48:49], v114, s68, v[122:123]
	v_pk_mul_f32 v[82:83], v[106:107], v[82:83] op_sel_hi:[0,1]
	v_pk_mul_f32 v[84:85], v[106:107], v[84:85] op_sel_hi:[0,1]
	v_pk_mul_f32 v[90:91], v[106:107], v[90:91] op_sel_hi:[0,1]
	v_pk_mul_f32 v[92:93], v[106:107], v[92:93] op_sel_hi:[0,1]
	v_lshl_add_u64 v[100:101], v[100:101], 0, s[46:47]
	v_pk_mul_f32 v[84:85], v[96:97], v[84:85]
	v_pk_mul_f32 v[82:83], v[94:95], v[82:83]
	v_pk_mul_f32 v[88:89], v[88:89], v[92:93]
	v_pk_mul_f32 v[86:87], v[86:87], v[90:91]
	v_lshl_add_u64 v[100:101], v[100:101], 0, v[138:139]
	v_cvt_pk_bf16_f32 v82, v82, v83
	v_cvt_pk_bf16_f32 v83, v84, v85
	v_cvt_pk_bf16_f32 v84, v86, v87
	v_cvt_pk_bf16_f32 v85, v88, v89
	global_store_dwordx4 v[100:101], v[82:85], off
	s_nop 0
	s_nop 0
	v_add_u32_e32 v84, 0x80, v148
	v_mad_i64_i32 v[82:83], s[48:49], v98, s68, v[122:123]
	v_lshl_add_u64 v[82:83], v[82:83], 0, s[46:47]
	v_lshl_add_u64 v[82:83], v[82:83], 0, v[138:139]
	v_fmamk_f32 v85, v234, 0x3a800000, v158
	v_rsq_f32_e32 v89, v85
	s_nop 0
	v_mul_f32_e32 v88, 0xbfb8aa3b, v89
	v_pk_mul_f32 v[76:77], v[76:77], v[88:89] op_sel_hi:[1,0]
	v_pk_mul_f32 v[74:75], v[74:75], v[88:89] op_sel_hi:[1,0]
	v_pk_mul_f32 v[68:69], v[68:69], v[88:89] op_sel_hi:[1,0]
	v_pk_mul_f32 v[66:67], v[66:67], v[88:89] op_sel_hi:[1,0]
	v_exp_f32_e32 v74, v74
	v_exp_f32_e32 v75, v75
	v_exp_f32_e32 v76, v76
	v_exp_f32_e32 v77, v77
	v_exp_f32_e32 v66, v66
	v_exp_f32_e32 v67, v67
	v_exp_f32_e32 v68, v68
	v_exp_f32_e32 v69, v69
	v_mul_f32_e32 v90, v89, v89
	v_add_f32_e32 v74, 1.0, v74
	v_add_f32_e32 v75, 1.0, v75
	v_add_f32_e32 v76, 1.0, v76
	v_add_f32_e32 v77, 1.0, v77
	v_add_f32_e32 v85, 1.0, v66
	v_add_f32_e32 v88, 1.0, v67
	v_add_f32_e32 v89, 1.0, v68
	v_add_f32_e32 v91, 1.0, v69
	v_rcp_f32_e32 v66, v74
	v_rcp_f32_e32 v67, v75
	v_rcp_f32_e32 v68, v76
	v_rcp_f32_e32 v69, v77
	v_rcp_f32_e32 v74, v85
	v_rcp_f32_e32 v75, v88
	v_rcp_f32_e32 v76, v89
	v_rcp_f32_e32 v77, v91
	v_pk_mul_f32 v[66:67], v[90:91], v[66:67] op_sel_hi:[0,1]
	v_pk_mul_f32 v[68:69], v[90:91], v[68:69] op_sel_hi:[0,1]
	v_pk_mul_f32 v[74:75], v[90:91], v[74:75] op_sel_hi:[0,1]
	v_pk_mul_f32 v[76:77], v[90:91], v[76:77] op_sel_hi:[0,1]
	v_pk_mul_f32 v[68:69], v[80:81], v[68:69]
	v_pk_mul_f32 v[66:67], v[78:79], v[66:67]
	v_pk_mul_f32 v[72:73], v[72:73], v[76:77]
	v_pk_mul_f32 v[70:71], v[70:71], v[74:75]
	v_cvt_pk_bf16_f32 v66, v66, v67
	v_cvt_pk_bf16_f32 v67, v68, v69
	v_cvt_pk_bf16_f32 v68, v70, v71
	v_cvt_pk_bf16_f32 v69, v72, v73
	global_store_dwordx4 v[82:83], v[66:69], off
	v_fmamk_f32 v70, v235, 0x3a800000, v158
	v_rsq_f32_e32 v73, v70
	v_add_u32_e32 v66, 0x90, v148
	v_mul_f32_e32 v72, 0xbfb8aa3b, v73
	v_pk_mul_f32 v[60:61], v[60:61], v[72:73] op_sel_hi:[1,0]
	v_pk_mul_f32 v[58:59], v[58:59], v[72:73] op_sel_hi:[1,0]
	v_pk_mul_f32 v[52:53], v[52:53], v[72:73] op_sel_hi:[1,0]
	v_pk_mul_f32 v[50:51], v[50:51], v[72:73] op_sel_hi:[1,0]
	v_exp_f32_e32 v58, v58
	v_exp_f32_e32 v59, v59
	v_exp_f32_e32 v60, v60
	v_exp_f32_e32 v61, v61
	v_exp_f32_e32 v50, v50
	v_exp_f32_e32 v51, v51
	v_exp_f32_e32 v52, v52
	v_exp_f32_e32 v53, v53
	v_mul_f32_e32 v74, v73, v73
	v_add_f32_e32 v58, 1.0, v58
	v_add_f32_e32 v59, 1.0, v59
	v_add_f32_e32 v60, 1.0, v60
	v_add_f32_e32 v61, 1.0, v61
	v_add_f32_e32 v67, 1.0, v50
	v_add_f32_e32 v72, 1.0, v51
	v_add_f32_e32 v73, 1.0, v52
	v_add_f32_e32 v75, 1.0, v53
	v_rcp_f32_e32 v50, v58
	v_rcp_f32_e32 v51, v59
	v_rcp_f32_e32 v52, v60
	v_rcp_f32_e32 v53, v61
	v_rcp_f32_e32 v58, v67
	v_rcp_f32_e32 v59, v72
	v_rcp_f32_e32 v60, v73
	v_rcp_f32_e32 v61, v75
	v_mad_i64_i32 v[68:69], s[48:49], v84, s68, v[122:123]
	v_pk_mul_f32 v[50:51], v[74:75], v[50:51] op_sel_hi:[0,1]
	v_pk_mul_f32 v[52:53], v[74:75], v[52:53] op_sel_hi:[0,1]
	v_pk_mul_f32 v[58:59], v[74:75], v[58:59] op_sel_hi:[0,1]
	v_pk_mul_f32 v[60:61], v[74:75], v[60:61] op_sel_hi:[0,1]
	v_lshl_add_u64 v[68:69], v[68:69], 0, s[46:47]
	v_pk_mul_f32 v[52:53], v[64:65], v[52:53]
	v_pk_mul_f32 v[50:51], v[62:63], v[50:51]
	v_pk_mul_f32 v[56:57], v[56:57], v[60:61]
	v_pk_mul_f32 v[54:55], v[54:55], v[58:59]
	v_lshl_add_u64 v[68:69], v[68:69], 0, v[138:139]
	v_cvt_pk_bf16_f32 v50, v50, v51
	v_cvt_pk_bf16_f32 v51, v52, v53
	v_cvt_pk_bf16_f32 v52, v54, v55
	v_cvt_pk_bf16_f32 v53, v56, v57
	global_store_dwordx4 v[68:69], v[50:53], off
	v_fmamk_f32 v54, v236, 0x3a800000, v158
	v_rsq_f32_e32 v57, v54
	v_add_u32_e32 v50, 0xa0, v148
	v_mul_f32_e32 v56, 0xbfb8aa3b, v57
	v_pk_mul_f32 v[44:45], v[44:45], v[56:57] op_sel_hi:[1,0]
	v_pk_mul_f32 v[42:43], v[42:43], v[56:57] op_sel_hi:[1,0]
	v_pk_mul_f32 v[36:37], v[36:37], v[56:57] op_sel_hi:[1,0]
	v_pk_mul_f32 v[34:35], v[34:35], v[56:57] op_sel_hi:[1,0]
	v_exp_f32_e32 v42, v42
	v_exp_f32_e32 v43, v43
	v_exp_f32_e32 v44, v44
	v_exp_f32_e32 v45, v45
	v_exp_f32_e32 v34, v34
	v_exp_f32_e32 v35, v35
	v_exp_f32_e32 v36, v36
	v_exp_f32_e32 v37, v37
	v_mul_f32_e32 v58, v57, v57
	v_add_f32_e32 v42, 1.0, v42
	v_add_f32_e32 v43, 1.0, v43
	v_add_f32_e32 v44, 1.0, v44
	v_add_f32_e32 v45, 1.0, v45
	v_add_f32_e32 v51, 1.0, v34
	v_add_f32_e32 v56, 1.0, v35
	v_add_f32_e32 v57, 1.0, v36
	v_add_f32_e32 v59, 1.0, v37
	v_rcp_f32_e32 v34, v42
	v_rcp_f32_e32 v35, v43
	v_rcp_f32_e32 v36, v44
	v_rcp_f32_e32 v37, v45
	v_rcp_f32_e32 v42, v51
	v_rcp_f32_e32 v43, v56
	v_rcp_f32_e32 v44, v57
	v_rcp_f32_e32 v45, v59
	v_mad_i64_i32 v[52:53], s[48:49], v66, s68, v[122:123]
	v_pk_mul_f32 v[34:35], v[58:59], v[34:35] op_sel_hi:[0,1]
	v_pk_mul_f32 v[36:37], v[58:59], v[36:37] op_sel_hi:[0,1]
	v_pk_mul_f32 v[42:43], v[58:59], v[42:43] op_sel_hi:[0,1]
	v_pk_mul_f32 v[44:45], v[58:59], v[44:45] op_sel_hi:[0,1]
	v_lshl_add_u64 v[52:53], v[52:53], 0, s[46:47]
	v_pk_mul_f32 v[36:37], v[48:49], v[36:37]
	v_pk_mul_f32 v[34:35], v[46:47], v[34:35]
	v_pk_mul_f32 v[40:41], v[40:41], v[44:45]
	v_pk_mul_f32 v[38:39], v[38:39], v[42:43]
	v_lshl_add_u64 v[52:53], v[52:53], 0, v[138:139]
	v_cvt_pk_bf16_f32 v34, v34, v35
	v_cvt_pk_bf16_f32 v35, v36, v37
	v_cvt_pk_bf16_f32 v36, v38, v39
	v_cvt_pk_bf16_f32 v37, v40, v41
	global_store_dwordx4 v[52:53], v[34:37], off
	v_fmamk_f32 v38, v237, 0x3a800000, v158
	v_rsq_f32_e32 v41, v38
	v_add_u32_e32 v34, 0xb0, v148
	v_mul_f32_e32 v40, 0xbfb8aa3b, v41
	v_pk_mul_f32 v[28:29], v[28:29], v[40:41] op_sel_hi:[1,0]
	v_pk_mul_f32 v[26:27], v[26:27], v[40:41] op_sel_hi:[1,0]
	v_pk_mul_f32 v[20:21], v[20:21], v[40:41] op_sel_hi:[1,0]
	v_pk_mul_f32 v[18:19], v[18:19], v[40:41] op_sel_hi:[1,0]
	v_exp_f32_e32 v26, v26
	v_exp_f32_e32 v27, v27
	v_exp_f32_e32 v28, v28
	v_exp_f32_e32 v29, v29
	v_exp_f32_e32 v18, v18
	v_exp_f32_e32 v19, v19
	v_exp_f32_e32 v20, v20
	v_exp_f32_e32 v21, v21
	v_mul_f32_e32 v42, v41, v41
	v_add_f32_e32 v26, 1.0, v26
	v_add_f32_e32 v27, 1.0, v27
	v_add_f32_e32 v28, 1.0, v28
	v_add_f32_e32 v29, 1.0, v29
	v_add_f32_e32 v35, 1.0, v18
	v_add_f32_e32 v40, 1.0, v19
	v_add_f32_e32 v41, 1.0, v20
	v_add_f32_e32 v43, 1.0, v21
	v_rcp_f32_e32 v18, v26
	v_rcp_f32_e32 v19, v27
	v_rcp_f32_e32 v20, v28
	v_rcp_f32_e32 v21, v29
	v_rcp_f32_e32 v26, v35
	v_rcp_f32_e32 v27, v40
	v_rcp_f32_e32 v28, v41
	v_rcp_f32_e32 v29, v43
	v_mad_i64_i32 v[36:37], s[48:49], v50, s68, v[122:123]
	v_pk_mul_f32 v[18:19], v[42:43], v[18:19] op_sel_hi:[0,1]
	v_pk_mul_f32 v[20:21], v[42:43], v[20:21] op_sel_hi:[0,1]
	v_pk_mul_f32 v[26:27], v[42:43], v[26:27] op_sel_hi:[0,1]
	v_pk_mul_f32 v[28:29], v[42:43], v[28:29] op_sel_hi:[0,1]
	v_lshl_add_u64 v[36:37], v[36:37], 0, s[46:47]
	v_pk_mul_f32 v[20:21], v[32:33], v[20:21]
	v_pk_mul_f32 v[18:19], v[30:31], v[18:19]
	v_pk_mul_f32 v[24:25], v[24:25], v[28:29]
	v_pk_mul_f32 v[22:23], v[22:23], v[26:27]
	v_lshl_add_u64 v[36:37], v[36:37], 0, v[138:139]
	v_cvt_pk_bf16_f32 v18, v18, v19
	v_cvt_pk_bf16_f32 v19, v20, v21
	v_cvt_pk_bf16_f32 v20, v22, v23
	v_cvt_pk_bf16_f32 v21, v24, v25
	global_store_dwordx4 v[36:37], v[18:21], off
	s_nop 0
	s_nop 0
	v_fmamk_f32 v18, v238, 0x3a800000, v158
	v_rsq_f32_e32 v21, v18
	v_mad_i64_i32 v[18:19], s[4:5], v34, s68, v[122:123]
	v_lshl_add_u64 v[18:19], v[18:19], 0, s[46:47]
	v_mul_f32_e32 v20, 0xbfb8aa3b, v21
	v_pk_mul_f32 v[12:13], v[12:13], v[20:21] op_sel_hi:[1,0]
	v_pk_mul_f32 v[10:11], v[10:11], v[20:21] op_sel_hi:[1,0]
	v_pk_mul_f32 v[8:9], v[8:9], v[20:21] op_sel_hi:[1,0]
	v_pk_mul_f32 v[6:7], v[6:7], v[20:21] op_sel_hi:[1,0]
	v_exp_f32_e32 v10, v10
	v_exp_f32_e32 v11, v11
	v_exp_f32_e32 v12, v12
	v_exp_f32_e32 v13, v13
	v_exp_f32_e32 v6, v6
	v_exp_f32_e32 v7, v7
	v_exp_f32_e32 v8, v8
	v_exp_f32_e32 v9, v9
	v_mul_f32_e32 v22, v21, v21
	v_add_f32_e32 v10, 1.0, v10
	v_add_f32_e32 v11, 1.0, v11
	v_add_f32_e32 v12, 1.0, v12
	v_add_f32_e32 v13, 1.0, v13
	v_add_f32_e32 v20, 1.0, v6
	v_add_f32_e32 v21, 1.0, v7
	v_add_f32_e32 v23, 1.0, v8
	v_add_f32_e32 v24, 1.0, v9
	v_rcp_f32_e32 v6, v10
	v_rcp_f32_e32 v7, v11
	v_rcp_f32_e32 v8, v12
	v_rcp_f32_e32 v9, v13
	v_rcp_f32_e32 v10, v20
	v_rcp_f32_e32 v11, v21
	v_rcp_f32_e32 v12, v23
	v_rcp_f32_e32 v13, v24
	v_pk_mul_f32 v[6:7], v[22:23], v[6:7] op_sel_hi:[0,1]
	v_pk_mul_f32 v[8:9], v[22:23], v[8:9] op_sel_hi:[0,1]
	v_pk_mul_f32 v[10:11], v[22:23], v[10:11] op_sel_hi:[0,1]
	v_pk_mul_f32 v[12:13], v[22:23], v[12:13] op_sel_hi:[0,1]
	v_pk_mul_f32 v[8:9], v[16:17], v[8:9]
	v_pk_mul_f32 v[6:7], v[14:15], v[6:7]
	v_pk_mul_f32 v[12:13], v[4:5], v[12:13]
	v_pk_mul_f32 v[4:5], v[2:3], v[10:11]
	v_lshl_add_u64 v[18:19], v[18:19], 0, v[138:139]
	v_cvt_pk_bf16_f32 v2, v6, v7
	v_cvt_pk_bf16_f32 v3, v8, v9
	v_cvt_pk_bf16_f32 v4, v4, v5
	v_cvt_pk_bf16_f32 v5, v12, v13
	s_mov_b64 s[4:5], -1
	global_store_dwordx4 v[18:19], v[2:5], off
	s_cbranch_vccnz .LBB0_148
	s_andn2_b64 vcc, exec, s[10:11]
	s_cbranch_vccnz .LBB0_147
	s_barrier
	s_branch .LBB0_147

.LBB0_840:
	ds_read_b128 v[160:163], v155
	ds_read_b128 v[164:167], v155 offset:1024
	ds_read_b128 v[168:171], v155 offset:2048
	ds_read_b128 v[172:175], v155 offset:3072
	ds_read_b128 v[176:179], v156
	ds_read_b128 v[180:183], v156 offset:1024
	ds_read_b128 v[184:187], v156 offset:2048
	ds_read_b128 v[188:191], v156 offset:3072
	s_add_u32 s50, s48, 0xfffc0080
	s_addc_u32 s51, s49, -1
	s_cmp_eq_u32 s73, 12
	s_cselect_b32 s53, s27, s51
	s_cselect_b32 s52, s69, s50
	s_cselect_b32 s51, s25, s72
	s_cselect_b32 s50, s70, s71
	v_lshl_add_u64 v[148:149], s[48:49], 0, v[140:141]
	s_add_i32 m0, s57, 0xc000
	ds_read_b128 v[192:195], v157
	ds_read_b128 v[196:199], v157 offset:1024
	ds_read_b128 v[200:203], v157 offset:2048
	ds_read_b128 v[204:207], v157 offset:3072
	ds_read_b128 v[208:211], v157 offset:4096
	ds_read_b128 v[212:215], v157 offset:5120
	ds_read_b128 v[216:219], v157 offset:6144
	ds_read_b128 v[220:223], v157 offset:7168
	global_load_lds_dwordx4 v[148:149], off
	v_lshl_add_u64 v[148:149], s[48:49], 0, v[142:143]
	s_add_i32 m0, s57, 0xe000
	s_nop 0
	global_load_lds_dwordx4 v[148:149], off
	s_waitcnt vmcnt(8)
	s_waitcnt lgkmcnt(0)
	s_barrier
	s_setprio 1
	s_waitcnt lgkmcnt(0)
	v_mfma_f32_16x16x32_bf16 v[118:121], v[160:163], v[192:195], v[118:121]
	v_mfma_f32_16x16x32_bf16 v[114:117], v[168:171], v[192:195], v[114:117]
	v_mfma_f32_16x16x32_bf16 v[106:109], v[160:163], v[200:203], v[106:109]
	v_mfma_f32_16x16x32_bf16 v[98:101], v[168:171], v[200:203], v[98:101]
	v_mfma_f32_16x16x32_bf16 v[90:93], v[160:163], v[208:211], v[90:93]
	v_mfma_f32_16x16x32_bf16 v[82:85], v[168:171], v[208:211], v[82:85]
	v_mfma_f32_16x16x32_bf16 v[74:77], v[160:163], v[216:219], v[74:77]
	v_mfma_f32_16x16x32_bf16 v[66:69], v[168:171], v[216:219], v[66:69]
	v_mfma_f32_16x16x32_bf16 v[118:121], v[164:167], v[196:199], v[118:121]
	v_mfma_f32_16x16x32_bf16 v[114:117], v[172:175], v[196:199], v[114:117]
	v_mfma_f32_16x16x32_bf16 v[106:109], v[164:167], v[204:207], v[106:109]
	v_mfma_f32_16x16x32_bf16 v[98:101], v[172:175], v[204:207], v[98:101]
	v_mfma_f32_16x16x32_bf16 v[90:93], v[164:167], v[212:215], v[90:93]
	v_mfma_f32_16x16x32_bf16 v[82:85], v[172:175], v[212:215], v[82:85]
	v_mfma_f32_16x16x32_bf16 v[74:77], v[164:167], v[220:223], v[74:77]
	v_mfma_f32_16x16x32_bf16 v[66:69], v[172:175], v[220:223], v[66:69]
	s_setprio 0
	s_setprio 1
	v_mfma_f32_16x16x32_bf16 v[126:129], v[176:179], v[192:195], v[126:129]
	v_mfma_f32_16x16x32_bf16 v[122:125], v[184:187], v[192:195], v[122:125]
	v_mfma_f32_16x16x32_bf16 v[110:113], v[176:179], v[200:203], v[110:113]
	v_mfma_f32_16x16x32_bf16 v[102:105], v[184:187], v[200:203], v[102:105]
	v_mfma_f32_16x16x32_bf16 v[94:97], v[176:179], v[208:211], v[94:97]
	v_mfma_f32_16x16x32_bf16 v[86:89], v[184:187], v[208:211], v[86:89]
	v_mfma_f32_16x16x32_bf16 v[78:81], v[176:179], v[216:219], v[78:81]
	v_mfma_f32_16x16x32_bf16 v[70:73], v[184:187], v[216:219], v[70:73]
	v_mfma_f32_16x16x32_bf16 v[126:129], v[180:183], v[196:199], v[126:129]
	v_mfma_f32_16x16x32_bf16 v[122:125], v[188:191], v[196:199], v[122:125]
	v_mfma_f32_16x16x32_bf16 v[110:113], v[180:183], v[204:207], v[110:113]
	v_mfma_f32_16x16x32_bf16 v[102:105], v[188:191], v[204:207], v[102:105]
	v_mfma_f32_16x16x32_bf16 v[94:97], v[180:183], v[212:215], v[94:97]
	v_mfma_f32_16x16x32_bf16 v[86:89], v[188:191], v[212:215], v[86:89]
	v_mfma_f32_16x16x32_bf16 v[78:81], v[180:183], v[220:223], v[78:81]
	v_mfma_f32_16x16x32_bf16 v[70:73], v[188:191], v[220:223], v[70:73]
	s_setprio 0
	s_barrier
	s_add_i32 s74, s66, s54
	v_lshl_add_u64 v[148:149], s[50:51], 0, v[134:135]
	s_mov_b32 m0, s74
	ds_read_b128 v[192:195], v157 offset:16384
	ds_read_b128 v[196:199], v157 offset:17408
	ds_read_b128 v[200:203], v157 offset:18432
	ds_read_b128 v[204:207], v157 offset:19456
	ds_read_b128 v[208:211], v157 offset:20480
	ds_read_b128 v[212:215], v157 offset:21504
	ds_read_b128 v[216:219], v157 offset:22528
	ds_read_b128 v[220:223], v157 offset:23552
	global_load_lds_dwordx4 v[148:149], off
	s_add_i32 m0, s74, 0x2000
	s_add_u32 s74, s50, 0x40000
	v_lshl_add_u64 v[224:225], s[50:51], 0, v[130:131]
	s_addc_u32 s75, s51, 0
	s_add_i32 s76, s67, s54
	global_load_lds_dwordx4 v[224:225], off
	v_lshl_add_u64 v[226:227], s[74:75], 0, v[134:135]
	s_mov_b32 m0, s76
	v_lshl_add_u64 v[228:229], s[52:53], 0, v[132:133]
	global_load_lds_dwordx4 v[226:227], off
	v_lshl_add_u64 v[226:227], s[74:75], 0, v[130:131]
	s_add_i32 m0, s76, 0x2000
	s_nop 0
	global_load_lds_dwordx4 v[226:227], off
	v_lshl_add_u64 v[226:227], s[52:53], 0, v[136:137]
	s_mov_b32 m0, s57
	s_nop 0
	global_load_lds_dwordx4 v[226:227], off
	s_mov_b32 m0, s58
	s_nop 0
	global_load_lds_dwordx4 v[228:229], off
	s_waitcnt vmcnt(8)
	s_waitcnt lgkmcnt(0)
	s_barrier
	s_setprio 1
	s_waitcnt lgkmcnt(0)
	v_mfma_f32_16x16x32_bf16 v[58:61], v[160:163], v[192:195], v[58:61]
	v_mfma_f32_16x16x32_bf16 v[50:53], v[168:171], v[192:195], v[50:53]
	v_mfma_f32_16x16x32_bf16 v[42:45], v[160:163], v[200:203], v[42:45]
	v_mfma_f32_16x16x32_bf16 v[34:37], v[168:171], v[200:203], v[34:37]
	v_mfma_f32_16x16x32_bf16 v[26:29], v[160:163], v[208:211], v[26:29]
	v_mfma_f32_16x16x32_bf16 v[18:21], v[168:171], v[208:211], v[18:21]
	v_mfma_f32_16x16x32_bf16 v[10:13], v[160:163], v[216:219], v[10:13]
	v_mfma_f32_16x16x32_bf16 v[6:9], v[168:171], v[216:219], v[6:9]
	v_mfma_f32_16x16x32_bf16 v[58:61], v[164:167], v[196:199], v[58:61]
	v_mfma_f32_16x16x32_bf16 v[50:53], v[172:175], v[196:199], v[50:53]
	v_mfma_f32_16x16x32_bf16 v[42:45], v[164:167], v[204:207], v[42:45]
	v_mfma_f32_16x16x32_bf16 v[34:37], v[172:175], v[204:207], v[34:37]
	v_mfma_f32_16x16x32_bf16 v[26:29], v[164:167], v[212:215], v[26:29]
	v_mfma_f32_16x16x32_bf16 v[18:21], v[172:175], v[212:215], v[18:21]
	v_mfma_f32_16x16x32_bf16 v[10:13], v[164:167], v[220:223], v[10:13]
	v_mfma_f32_16x16x32_bf16 v[6:9], v[172:175], v[220:223], v[6:9]
	s_setprio 0
	s_setprio 1
	v_mfma_f32_16x16x32_bf16 v[62:65], v[176:179], v[192:195], v[62:65]
	v_mfma_f32_16x16x32_bf16 v[54:57], v[184:187], v[192:195], v[54:57]
	v_mfma_f32_16x16x32_bf16 v[46:49], v[176:179], v[200:203], v[46:49]
	v_mfma_f32_16x16x32_bf16 v[38:41], v[184:187], v[200:203], v[38:41]
	v_mfma_f32_16x16x32_bf16 v[30:33], v[176:179], v[208:211], v[30:33]
	v_mfma_f32_16x16x32_bf16 v[22:25], v[184:187], v[208:211], v[22:25]
	v_mfma_f32_16x16x32_bf16 v[14:17], v[176:179], v[216:219], v[14:17]
	v_mfma_f32_16x16x32_bf16 v[2:5], v[184:187], v[216:219], v[2:5]
	v_mfma_f32_16x16x32_bf16 v[62:65], v[180:183], v[196:199], v[62:65]
	v_mfma_f32_16x16x32_bf16 v[54:57], v[188:191], v[196:199], v[54:57]
	v_mfma_f32_16x16x32_bf16 v[46:49], v[180:183], v[204:207], v[46:49]
	v_mfma_f32_16x16x32_bf16 v[38:41], v[188:191], v[204:207], v[38:41]
	v_mfma_f32_16x16x32_bf16 v[30:33], v[180:183], v[212:215], v[30:33]
	v_mfma_f32_16x16x32_bf16 v[22:25], v[188:191], v[212:215], v[22:25]
	v_mfma_f32_16x16x32_bf16 v[14:17], v[180:183], v[220:223], v[14:17]
	v_mfma_f32_16x16x32_bf16 v[2:5], v[188:191], v[220:223], v[2:5]
	s_setprio 0
	s_barrier
	s_add_i32 s74, 0, 0x18000
	v_add_u32_e32 v159, s74, v151
	s_add_i32 s75, 0, 0x1c000
	ds_read_b128 v[160:163], v159
	ds_read_b128 v[164:167], v159 offset:1024
	ds_read_b128 v[168:171], v159 offset:2048
	ds_read_b128 v[172:175], v159 offset:3072
	v_add_u32_e32 v159, s75, v151
	ds_read_b128 v[176:179], v159
	ds_read_b128 v[180:183], v159 offset:1024
	ds_read_b128 v[184:187], v159 offset:2048
	ds_read_b128 v[188:191], v159 offset:3072
	s_add_u32 s52, s52, 0x40000
	s_addc_u32 s53, s53, 0
	s_mov_b32 m0, s59
	v_lshl_add_u64 v[230:231], s[52:53], 0, v[136:137]
	ds_read_b128 v[192:195], v157 offset:32768
	ds_read_b128 v[196:199], v157 offset:33792
	ds_read_b128 v[200:203], v157 offset:34816
	ds_read_b128 v[204:207], v157 offset:35840
	ds_read_b128 v[208:211], v157 offset:36864
	ds_read_b128 v[212:215], v157 offset:37888
	ds_read_b128 v[216:219], v157 offset:38912
	ds_read_b128 v[220:223], v157 offset:39936
	global_load_lds_dwordx4 v[230:231], off
	v_lshl_add_u64 v[230:231], s[52:53], 0, v[132:133]
	s_mov_b32 m0, s60
	s_nop 0
	global_load_lds_dwordx4 v[230:231], off
	s_waitcnt vmcnt(8)
	s_waitcnt lgkmcnt(0)
	s_barrier
	s_setprio 1
	s_waitcnt lgkmcnt(0)
	v_mfma_f32_16x16x32_bf16 v[118:121], v[160:163], v[192:195], v[118:121]
	v_mfma_f32_16x16x32_bf16 v[114:117], v[168:171], v[192:195], v[114:117]
	v_mfma_f32_16x16x32_bf16 v[106:109], v[160:163], v[200:203], v[106:109]
	v_mfma_f32_16x16x32_bf16 v[98:101], v[168:171], v[200:203], v[98:101]
	v_mfma_f32_16x16x32_bf16 v[90:93], v[160:163], v[208:211], v[90:93]
	v_mfma_f32_16x16x32_bf16 v[82:85], v[168:171], v[208:211], v[82:85]
	v_mfma_f32_16x16x32_bf16 v[74:77], v[160:163], v[216:219], v[74:77]
	v_mfma_f32_16x16x32_bf16 v[66:69], v[168:171], v[216:219], v[66:69]
	v_mfma_f32_16x16x32_bf16 v[118:121], v[164:167], v[196:199], v[118:121]
	v_mfma_f32_16x16x32_bf16 v[114:117], v[172:175], v[196:199], v[114:117]
	v_mfma_f32_16x16x32_bf16 v[106:109], v[164:167], v[204:207], v[106:109]
	v_mfma_f32_16x16x32_bf16 v[98:101], v[172:175], v[204:207], v[98:101]
	v_mfma_f32_16x16x32_bf16 v[90:93], v[164:167], v[212:215], v[90:93]
	v_mfma_f32_16x16x32_bf16 v[82:85], v[172:175], v[212:215], v[82:85]
	v_mfma_f32_16x16x32_bf16 v[74:77], v[164:167], v[220:223], v[74:77]
	v_mfma_f32_16x16x32_bf16 v[66:69], v[172:175], v[220:223], v[66:69]
	s_setprio 0
	s_setprio 1
	v_mfma_f32_16x16x32_bf16 v[126:129], v[176:179], v[192:195], v[126:129]
	v_mfma_f32_16x16x32_bf16 v[122:125], v[184:187], v[192:195], v[122:125]
	v_mfma_f32_16x16x32_bf16 v[110:113], v[176:179], v[200:203], v[110:113]
	v_mfma_f32_16x16x32_bf16 v[102:105], v[184:187], v[200:203], v[102:105]
	v_mfma_f32_16x16x32_bf16 v[94:97], v[176:179], v[208:211], v[94:97]
	v_mfma_f32_16x16x32_bf16 v[86:89], v[184:187], v[208:211], v[86:89]
	v_mfma_f32_16x16x32_bf16 v[78:81], v[176:179], v[216:219], v[78:81]
	v_mfma_f32_16x16x32_bf16 v[70:73], v[184:187], v[216:219], v[70:73]
	v_mfma_f32_16x16x32_bf16 v[126:129], v[180:183], v[196:199], v[126:129]
	v_mfma_f32_16x16x32_bf16 v[122:125], v[188:191], v[196:199], v[122:125]
	v_mfma_f32_16x16x32_bf16 v[110:113], v[180:183], v[204:207], v[110:113]
	v_mfma_f32_16x16x32_bf16 v[102:105], v[188:191], v[204:207], v[102:105]
	v_mfma_f32_16x16x32_bf16 v[94:97], v[180:183], v[212:215], v[94:97]
	v_mfma_f32_16x16x32_bf16 v[86:89], v[188:191], v[212:215], v[86:89]
	v_mfma_f32_16x16x32_bf16 v[78:81], v[180:183], v[220:223], v[78:81]
	v_mfma_f32_16x16x32_bf16 v[70:73], v[188:191], v[220:223], v[70:73]
	s_setprio 0
	s_barrier
	s_add_i32 s52, s74, s54
	v_lshl_add_u64 v[148:149], v[148:149], 0, s[14:15]
	s_mov_b32 m0, s52
	ds_read_b128 v[192:195], v157 offset:49152
	ds_read_b128 v[196:199], v157 offset:50176
	ds_read_b128 v[200:203], v157 offset:51200
	ds_read_b128 v[204:207], v157 offset:52224
	ds_read_b128 v[208:211], v157 offset:53248
	ds_read_b128 v[212:215], v157 offset:54272
	ds_read_b128 v[216:219], v157 offset:55296
	ds_read_b128 v[220:223], v157 offset:56320
	global_load_lds_dwordx4 v[148:149], off
	s_add_i32 m0, s52, 0x2000
	s_add_u32 s50, s50, 0x40080
	v_lshl_add_u64 v[148:149], v[224:225], 0, s[14:15]
	s_addc_u32 s51, s51, 0
	s_add_i32 s52, s75, s54
	global_load_lds_dwordx4 v[148:149], off
	v_lshl_add_u64 v[148:149], s[50:51], 0, v[134:135]
	s_mov_b32 m0, s52
	s_nop 0
	global_load_lds_dwordx4 v[148:149], off
	v_lshl_add_u64 v[148:149], s[50:51], 0, v[130:131]
	s_add_i32 m0, s52, 0x2000
	s_nop 0
	global_load_lds_dwordx4 v[148:149], off
	v_lshl_add_u64 v[148:149], v[226:227], 0, s[14:15]
	s_mov_b32 m0, s62
	s_nop 0
	global_load_lds_dwordx4 v[148:149], off
	v_lshl_add_u64 v[148:149], v[228:229], 0, s[14:15]
	s_mov_b32 m0, s63
	s_nop 0
	global_load_lds_dwordx4 v[148:149], off
	s_waitcnt vmcnt(8)
	s_waitcnt lgkmcnt(0)
	s_barrier
	s_setprio 1
	s_waitcnt lgkmcnt(0)
	v_mfma_f32_16x16x32_bf16 v[58:61], v[160:163], v[192:195], v[58:61]
	v_mfma_f32_16x16x32_bf16 v[50:53], v[168:171], v[192:195], v[50:53]
	v_mfma_f32_16x16x32_bf16 v[42:45], v[160:163], v[200:203], v[42:45]
	v_mfma_f32_16x16x32_bf16 v[34:37], v[168:171], v[200:203], v[34:37]
	v_mfma_f32_16x16x32_bf16 v[26:29], v[160:163], v[208:211], v[26:29]
	v_mfma_f32_16x16x32_bf16 v[18:21], v[168:171], v[208:211], v[18:21]
	v_mfma_f32_16x16x32_bf16 v[10:13], v[160:163], v[216:219], v[10:13]
	v_mfma_f32_16x16x32_bf16 v[6:9], v[168:171], v[216:219], v[6:9]
	v_mfma_f32_16x16x32_bf16 v[58:61], v[164:167], v[196:199], v[58:61]
	v_mfma_f32_16x16x32_bf16 v[50:53], v[172:175], v[196:199], v[50:53]
	v_mfma_f32_16x16x32_bf16 v[42:45], v[164:167], v[204:207], v[42:45]
	v_mfma_f32_16x16x32_bf16 v[34:37], v[172:175], v[204:207], v[34:37]
	v_mfma_f32_16x16x32_bf16 v[26:29], v[164:167], v[212:215], v[26:29]
	v_mfma_f32_16x16x32_bf16 v[18:21], v[172:175], v[212:215], v[18:21]
	v_mfma_f32_16x16x32_bf16 v[10:13], v[164:167], v[220:223], v[10:13]
	v_mfma_f32_16x16x32_bf16 v[6:9], v[172:175], v[220:223], v[6:9]
	s_setprio 0
	s_setprio 1
	v_mfma_f32_16x16x32_bf16 v[62:65], v[176:179], v[192:195], v[62:65]
	v_mfma_f32_16x16x32_bf16 v[54:57], v[184:187], v[192:195], v[54:57]
	v_mfma_f32_16x16x32_bf16 v[46:49], v[176:179], v[200:203], v[46:49]
	v_mfma_f32_16x16x32_bf16 v[38:41], v[184:187], v[200:203], v[38:41]
	v_mfma_f32_16x16x32_bf16 v[30:33], v[176:179], v[208:211], v[30:33]
	v_mfma_f32_16x16x32_bf16 v[22:25], v[184:187], v[208:211], v[22:25]
	v_mfma_f32_16x16x32_bf16 v[14:17], v[176:179], v[216:219], v[14:17]
	v_mfma_f32_16x16x32_bf16 v[2:5], v[184:187], v[216:219], v[2:5]
	v_mfma_f32_16x16x32_bf16 v[62:65], v[180:183], v[196:199], v[62:65]
	v_mfma_f32_16x16x32_bf16 v[54:57], v[188:191], v[196:199], v[54:57]
	v_mfma_f32_16x16x32_bf16 v[46:49], v[180:183], v[204:207], v[46:49]
	v_mfma_f32_16x16x32_bf16 v[38:41], v[188:191], v[204:207], v[38:41]
	v_mfma_f32_16x16x32_bf16 v[30:33], v[180:183], v[212:215], v[30:33]
	v_mfma_f32_16x16x32_bf16 v[22:25], v[188:191], v[212:215], v[22:25]
	v_mfma_f32_16x16x32_bf16 v[14:17], v[180:183], v[220:223], v[14:17]
	v_mfma_f32_16x16x32_bf16 v[2:5], v[188:191], v[220:223], v[2:5]
	s_setprio 0
	s_barrier
	s_add_i32 s73, s73, 2
	s_add_u32 s48, s48, 0x100
	s_addc_u32 s49, s49, 0
	s_add_u32 s71, s71, 0x100
	s_addc_u32 s72, s72, 0
	s_cmp_gt_u32 s73, 13
	s_cbranch_scc0 .LBB0_840
	s_lshl_b32 s25, s46, 8
	v_add_u32_e32 v148, s25, v150
	v_ashrrev_i32_e32 v149, 31, v148
	v_lshl_add_u64 v[160:161], v[148:149], 2, s[10:11]
	global_load_dword v149, v[160:161], off
	global_load_dword v232, v[160:161], off offset:64
	global_load_dword v233, v[160:161], off offset:128
	global_load_dword v234, v[160:161], off offset:192
	global_load_dword v235, v[160:161], off offset:512
	global_load_dword v236, v[160:161], off offset:576
	global_load_dword v237, v[160:161], off offset:640
	global_load_dword v238, v[160:161], off offset:704
	s_and_b64 vcc, exec, s[16:17]
	s_cbranch_vccz .LBB0_843
	s_barrier
.LBB0_843:
	v_pk_mul_f32 v[128:129], v[120:121], v[128:129]
	v_pk_mul_f32 v[126:127], v[118:119], v[126:127]
	v_pk_mul_f32 v[124:125], v[116:117], v[124:125]
	v_pk_mul_f32 v[160:161], v[114:115], v[122:123]
	v_add_u32_e32 v162, s25, v152
	s_lshl_b32 s46, s47, 7
	v_mov_b64_e32 v[122:123], s[12:13]
	s_ashr_i32 s47, s46, 31
	v_mad_i64_i32 v[164:165], s[48:49], v148, s68, v[122:123]
	s_lshl_b64 s[46:47], s[46:47], 1
	v_lshl_add_u64 v[164:165], v[164:165], 0, s[46:47]
	v_lshl_add_u64 v[164:165], v[164:165], 0, v[138:139]
	v_pk_mul_f32 v[112:113], v[108:109], v[112:113]
	v_pk_mul_f32 v[110:111], v[106:107], v[110:111]
	v_pk_mul_f32 v[104:105], v[100:101], v[104:105]
	v_pk_mul_f32 v[102:103], v[98:99], v[102:103]
	v_pk_mul_f32 v[96:97], v[92:93], v[96:97]
	v_pk_mul_f32 v[94:95], v[90:91], v[94:95]
	v_pk_mul_f32 v[88:89], v[84:85], v[88:89]
	v_pk_mul_f32 v[86:87], v[82:83], v[86:87]
	v_pk_mul_f32 v[80:81], v[76:77], v[80:81]
	v_pk_mul_f32 v[78:79], v[74:75], v[78:79]
	v_pk_mul_f32 v[72:73], v[68:69], v[72:73]
	v_pk_mul_f32 v[70:71], v[66:67], v[70:71]
	v_pk_mul_f32 v[64:65], v[60:61], v[64:65]
	v_pk_mul_f32 v[62:63], v[58:59], v[62:63]
	v_pk_mul_f32 v[56:57], v[52:53], v[56:57]
	v_pk_mul_f32 v[54:55], v[50:51], v[54:55]
	v_pk_mul_f32 v[48:49], v[44:45], v[48:49]
	v_pk_mul_f32 v[46:47], v[42:43], v[46:47]
	v_pk_mul_f32 v[40:41], v[36:37], v[40:41]
	v_pk_mul_f32 v[38:39], v[34:35], v[38:39]
	v_pk_mul_f32 v[32:33], v[28:29], v[32:33]
	v_pk_mul_f32 v[30:31], v[26:27], v[30:31]
	v_pk_mul_f32 v[24:25], v[20:21], v[24:25]
	v_pk_mul_f32 v[22:23], v[18:19], v[22:23]
	v_pk_mul_f32 v[16:17], v[12:13], v[16:17]
	v_pk_mul_f32 v[14:15], v[10:11], v[14:15]
	v_pk_mul_f32 v[4:5], v[8:9], v[4:5]
	v_pk_mul_f32 v[2:3], v[6:7], v[2:3]
	s_andn2_b64 vcc, exec, s[4:5]
	s_waitcnt vmcnt(0)
	v_fmamk_f32 v149, v149, 0x3a800000, v158
	v_rsq_f32_e32 v149, v149
	s_nop 0
	v_mul_f32_e32 v168, 0xbfb8aa3b, v149
	v_pk_mul_f32 v[120:121], v[120:121], v[168:169] op_sel_hi:[1,0]
	v_pk_mul_f32 v[118:119], v[118:119], v[168:169] op_sel_hi:[1,0]
	v_pk_mul_f32 v[116:117], v[116:117], v[168:169] op_sel_hi:[1,0]
	v_pk_mul_f32 v[114:115], v[114:115], v[168:169] op_sel_hi:[1,0]
	v_exp_f32_e32 v118, v118
	v_exp_f32_e32 v119, v119
	v_exp_f32_e32 v120, v120
	v_exp_f32_e32 v121, v121
	v_exp_f32_e32 v114, v114
	v_exp_f32_e32 v115, v115
	v_exp_f32_e32 v116, v116
	v_exp_f32_e32 v117, v117
	v_mul_f32_e32 v170, v149, v149
	v_add_f32_e32 v118, 1.0, v118
	v_add_f32_e32 v119, 1.0, v119
	v_add_f32_e32 v120, 1.0, v120
	v_add_f32_e32 v121, 1.0, v121
	v_add_f32_e32 v149, 1.0, v114
	v_add_f32_e32 v159, 1.0, v115
	v_add_f32_e32 v163, 1.0, v116
	v_add_f32_e32 v168, 1.0, v117
	v_rcp_f32_e32 v114, v118
	v_rcp_f32_e32 v115, v119
	v_rcp_f32_e32 v116, v120
	v_rcp_f32_e32 v117, v121
	v_rcp_f32_e32 v118, v149
	v_rcp_f32_e32 v119, v159
	v_rcp_f32_e32 v120, v163
	v_rcp_f32_e32 v121, v168
	v_pk_mul_f32 v[114:115], v[170:171], v[114:115] op_sel_hi:[0,1]
	v_pk_mul_f32 v[116:117], v[170:171], v[116:117] op_sel_hi:[0,1]
	v_pk_mul_f32 v[118:119], v[170:171], v[118:119] op_sel_hi:[0,1]
	v_pk_mul_f32 v[120:121], v[170:171], v[120:121] op_sel_hi:[0,1]
	v_pk_mul_f32 v[116:117], v[128:129], v[116:117]
	v_pk_mul_f32 v[114:115], v[126:127], v[114:115]
	v_pk_mul_f32 v[120:121], v[124:125], v[120:121]
	v_pk_mul_f32 v[118:119], v[160:161], v[118:119]
	v_cvt_pk_bf16_f32 v114, v114, v115
	v_cvt_pk_bf16_f32 v115, v116, v117
	v_cvt_pk_bf16_f32 v116, v118, v119
	v_cvt_pk_bf16_f32 v117, v120, v121
	global_store_dwordx4 v[164:165], v[114:117], off
	v_fmamk_f32 v118, v232, 0x3a800000, v158
	v_rsq_f32_e32 v121, v118
	v_add_u32_e32 v114, s25, v153
	v_mul_f32_e32 v120, 0xbfb8aa3b, v121
	v_pk_mul_f32 v[108:109], v[108:109], v[120:121] op_sel_hi:[1,0]
	v_pk_mul_f32 v[106:107], v[106:107], v[120:121] op_sel_hi:[1,0]
	v_pk_mul_f32 v[100:101], v[100:101], v[120:121] op_sel_hi:[1,0]
	v_pk_mul_f32 v[98:99], v[98:99], v[120:121] op_sel_hi:[1,0]
	v_exp_f32_e32 v106, v106
	v_exp_f32_e32 v107, v107
	v_exp_f32_e32 v108, v108
	v_exp_f32_e32 v109, v109
	v_exp_f32_e32 v98, v98
	v_exp_f32_e32 v99, v99
	v_exp_f32_e32 v100, v100
	v_exp_f32_e32 v101, v101
	v_mul_f32_e32 v124, v121, v121
	v_add_f32_e32 v106, 1.0, v106
	v_add_f32_e32 v107, 1.0, v107
	v_add_f32_e32 v108, 1.0, v108
	v_add_f32_e32 v109, 1.0, v109
	v_add_f32_e32 v115, 1.0, v98
	v_add_f32_e32 v120, 1.0, v99
	v_add_f32_e32 v121, 1.0, v100
	v_add_f32_e32 v125, 1.0, v101
	v_rcp_f32_e32 v98, v106
	v_rcp_f32_e32 v99, v107
	v_rcp_f32_e32 v100, v108
	v_rcp_f32_e32 v101, v109
	v_rcp_f32_e32 v106, v115
	v_rcp_f32_e32 v107, v120
	v_rcp_f32_e32 v108, v121
	v_rcp_f32_e32 v109, v125
	v_mad_i64_i32 v[116:117], s[48:49], v162, s68, v[122:123]
	v_pk_mul_f32 v[98:99], v[124:125], v[98:99] op_sel_hi:[0,1]
	v_pk_mul_f32 v[100:101], v[124:125], v[100:101] op_sel_hi:[0,1]
	v_pk_mul_f32 v[106:107], v[124:125], v[106:107] op_sel_hi:[0,1]
	v_pk_mul_f32 v[108:109], v[124:125], v[108:109] op_sel_hi:[0,1]
	v_lshl_add_u64 v[116:117], v[116:117], 0, s[46:47]
	v_pk_mul_f32 v[100:101], v[112:113], v[100:101]
	v_pk_mul_f32 v[98:99], v[110:111], v[98:99]
	v_pk_mul_f32 v[104:105], v[104:105], v[108:109]
	v_pk_mul_f32 v[102:103], v[102:103], v[106:107]
	v_lshl_add_u64 v[116:117], v[116:117], 0, v[138:139]
	v_cvt_pk_bf16_f32 v98, v98, v99
	v_cvt_pk_bf16_f32 v99, v100, v101
	v_cvt_pk_bf16_f32 v100, v102, v103
	v_cvt_pk_bf16_f32 v101, v104, v105
	global_store_dwordx4 v[116:117], v[98:101], off
	v_fmamk_f32 v102, v233, 0x3a800000, v158
	v_rsq_f32_e32 v105, v102
	v_add_u32_e32 v98, s25, v154
	v_mul_f32_e32 v104, 0xbfb8aa3b, v105
	v_pk_mul_f32 v[92:93], v[92:93], v[104:105] op_sel_hi:[1,0]
	v_pk_mul_f32 v[90:91], v[90:91], v[104:105] op_sel_hi:[1,0]
	v_pk_mul_f32 v[84:85], v[84:85], v[104:105] op_sel_hi:[1,0]
	v_pk_mul_f32 v[82:83], v[82:83], v[104:105] op_sel_hi:[1,0]
	v_exp_f32_e32 v90, v90
	v_exp_f32_e32 v91, v91
	v_exp_f32_e32 v92, v92
	v_exp_f32_e32 v93, v93
	v_exp_f32_e32 v82, v82
	v_exp_f32_e32 v83, v83
	v_exp_f32_e32 v84, v84
	v_exp_f32_e32 v85, v85
	v_mul_f32_e32 v106, v105, v105
	v_add_f32_e32 v90, 1.0, v90
	v_add_f32_e32 v91, 1.0, v91
	v_add_f32_e32 v92, 1.0, v92
	v_add_f32_e32 v93, 1.0, v93
	v_add_f32_e32 v99, 1.0, v82
	v_add_f32_e32 v104, 1.0, v83
	v_add_f32_e32 v105, 1.0, v84
	v_add_f32_e32 v107, 1.0, v85
	v_rcp_f32_e32 v82, v90
	v_rcp_f32_e32 v83, v91
	v_rcp_f32_e32 v84, v92
	v_rcp_f32_e32 v85, v93
	v_rcp_f32_e32 v90, v99
	v_rcp_f32_e32 v91, v104
	v_rcp_f32_e32 v92, v105
	v_rcp_f32_e32 v93, v107
	v_mad_i64_i32 v[100:101], s[48:49], v114, s68, v[122:123]
	v_pk_mul_f32 v[82:83], v[106:107], v[82:83] op_sel_hi:[0,1]
	v_pk_mul_f32 v[84:85], v[106:107], v[84:85] op_sel_hi:[0,1]
	v_pk_mul_f32 v[90:91], v[106:107], v[90:91] op_sel_hi:[0,1]
	v_pk_mul_f32 v[92:93], v[106:107], v[92:93] op_sel_hi:[0,1]
	v_lshl_add_u64 v[100:101], v[100:101], 0, s[46:47]
	v_pk_mul_f32 v[84:85], v[96:97], v[84:85]
	v_pk_mul_f32 v[82:83], v[94:95], v[82:83]
	v_pk_mul_f32 v[88:89], v[88:89], v[92:93]
	v_pk_mul_f32 v[86:87], v[86:87], v[90:91]
	v_lshl_add_u64 v[100:101], v[100:101], 0, v[138:139]
	v_cvt_pk_bf16_f32 v82, v82, v83
	v_cvt_pk_bf16_f32 v83, v84, v85
	v_cvt_pk_bf16_f32 v84, v86, v87
	v_cvt_pk_bf16_f32 v85, v88, v89
	global_store_dwordx4 v[100:101], v[82:85], off
	s_nop 0
	s_nop 0
	v_add_u32_e32 v84, 0x80, v148
	v_mad_i64_i32 v[82:83], s[48:49], v98, s68, v[122:123]
	v_lshl_add_u64 v[82:83], v[82:83], 0, s[46:47]
	v_lshl_add_u64 v[82:83], v[82:83], 0, v[138:139]
	v_fmamk_f32 v85, v234, 0x3a800000, v158
	v_rsq_f32_e32 v89, v85
	s_nop 0
	v_mul_f32_e32 v88, 0xbfb8aa3b, v89
	v_pk_mul_f32 v[76:77], v[76:77], v[88:89] op_sel_hi:[1,0]
	v_pk_mul_f32 v[74:75], v[74:75], v[88:89] op_sel_hi:[1,0]
	v_pk_mul_f32 v[68:69], v[68:69], v[88:89] op_sel_hi:[1,0]
	v_pk_mul_f32 v[66:67], v[66:67], v[88:89] op_sel_hi:[1,0]
	v_exp_f32_e32 v74, v74
	v_exp_f32_e32 v75, v75
	v_exp_f32_e32 v76, v76
	v_exp_f32_e32 v77, v77
	v_exp_f32_e32 v66, v66
	v_exp_f32_e32 v67, v67
	v_exp_f32_e32 v68, v68
	v_exp_f32_e32 v69, v69
	v_mul_f32_e32 v90, v89, v89
	v_add_f32_e32 v74, 1.0, v74
	v_add_f32_e32 v75, 1.0, v75
	v_add_f32_e32 v76, 1.0, v76
	v_add_f32_e32 v77, 1.0, v77
	v_add_f32_e32 v85, 1.0, v66
	v_add_f32_e32 v88, 1.0, v67
	v_add_f32_e32 v89, 1.0, v68
	v_add_f32_e32 v91, 1.0, v69
	v_rcp_f32_e32 v66, v74
	v_rcp_f32_e32 v67, v75
	v_rcp_f32_e32 v68, v76
	v_rcp_f32_e32 v69, v77
	v_rcp_f32_e32 v74, v85
	v_rcp_f32_e32 v75, v88
	v_rcp_f32_e32 v76, v89
	v_rcp_f32_e32 v77, v91
	v_pk_mul_f32 v[66:67], v[90:91], v[66:67] op_sel_hi:[0,1]
	v_pk_mul_f32 v[68:69], v[90:91], v[68:69] op_sel_hi:[0,1]
	v_pk_mul_f32 v[74:75], v[90:91], v[74:75] op_sel_hi:[0,1]
	v_pk_mul_f32 v[76:77], v[90:91], v[76:77] op_sel_hi:[0,1]
	v_pk_mul_f32 v[68:69], v[80:81], v[68:69]
	v_pk_mul_f32 v[66:67], v[78:79], v[66:67]
	v_pk_mul_f32 v[72:73], v[72:73], v[76:77]
	v_pk_mul_f32 v[70:71], v[70:71], v[74:75]
	v_cvt_pk_bf16_f32 v66, v66, v67
	v_cvt_pk_bf16_f32 v67, v68, v69
	v_cvt_pk_bf16_f32 v68, v70, v71
	v_cvt_pk_bf16_f32 v69, v72, v73
	global_store_dwordx4 v[82:83], v[66:69], off
	v_fmamk_f32 v70, v235, 0x3a800000, v158
	v_rsq_f32_e32 v73, v70
	v_add_u32_e32 v66, 0x90, v148
	v_mul_f32_e32 v72, 0xbfb8aa3b, v73
	v_pk_mul_f32 v[60:61], v[60:61], v[72:73] op_sel_hi:[1,0]
	v_pk_mul_f32 v[58:59], v[58:59], v[72:73] op_sel_hi:[1,0]
	v_pk_mul_f32 v[52:53], v[52:53], v[72:73] op_sel_hi:[1,0]
	v_pk_mul_f32 v[50:51], v[50:51], v[72:73] op_sel_hi:[1,0]
	v_exp_f32_e32 v58, v58
	v_exp_f32_e32 v59, v59
	v_exp_f32_e32 v60, v60
	v_exp_f32_e32 v61, v61
	v_exp_f32_e32 v50, v50
	v_exp_f32_e32 v51, v51
	v_exp_f32_e32 v52, v52
	v_exp_f32_e32 v53, v53
	v_mul_f32_e32 v74, v73, v73
	v_add_f32_e32 v58, 1.0, v58
	v_add_f32_e32 v59, 1.0, v59
	v_add_f32_e32 v60, 1.0, v60
	v_add_f32_e32 v61, 1.0, v61
	v_add_f32_e32 v67, 1.0, v50
	v_add_f32_e32 v72, 1.0, v51
	v_add_f32_e32 v73, 1.0, v52
	v_add_f32_e32 v75, 1.0, v53
	v_rcp_f32_e32 v50, v58
	v_rcp_f32_e32 v51, v59
	v_rcp_f32_e32 v52, v60
	v_rcp_f32_e32 v53, v61
	v_rcp_f32_e32 v58, v67
	v_rcp_f32_e32 v59, v72
	v_rcp_f32_e32 v60, v73
	v_rcp_f32_e32 v61, v75
	v_mad_i64_i32 v[68:69], s[48:49], v84, s68, v[122:123]
	v_pk_mul_f32 v[50:51], v[74:75], v[50:51] op_sel_hi:[0,1]
	v_pk_mul_f32 v[52:53], v[74:75], v[52:53] op_sel_hi:[0,1]
	v_pk_mul_f32 v[58:59], v[74:75], v[58:59] op_sel_hi:[0,1]
	v_pk_mul_f32 v[60:61], v[74:75], v[60:61] op_sel_hi:[0,1]
	v_lshl_add_u64 v[68:69], v[68:69], 0, s[46:47]
	v_pk_mul_f32 v[52:53], v[64:65], v[52:53]
	v_pk_mul_f32 v[50:51], v[62:63], v[50:51]
	v_pk_mul_f32 v[56:57], v[56:57], v[60:61]
	v_pk_mul_f32 v[54:55], v[54:55], v[58:59]
	v_lshl_add_u64 v[68:69], v[68:69], 0, v[138:139]
	v_cvt_pk_bf16_f32 v50, v50, v51
	v_cvt_pk_bf16_f32 v51, v52, v53
	v_cvt_pk_bf16_f32 v52, v54, v55
	v_cvt_pk_bf16_f32 v53, v56, v57
	global_store_dwordx4 v[68:69], v[50:53], off
	v_fmamk_f32 v54, v236, 0x3a800000, v158
	v_rsq_f32_e32 v57, v54
	v_add_u32_e32 v50, 0xa0, v148
	v_mul_f32_e32 v56, 0xbfb8aa3b, v57
	v_pk_mul_f32 v[44:45], v[44:45], v[56:57] op_sel_hi:[1,0]
	v_pk_mul_f32 v[42:43], v[42:43], v[56:57] op_sel_hi:[1,0]
	v_pk_mul_f32 v[36:37], v[36:37], v[56:57] op_sel_hi:[1,0]
	v_pk_mul_f32 v[34:35], v[34:35], v[56:57] op_sel_hi:[1,0]
	v_exp_f32_e32 v42, v42
	v_exp_f32_e32 v43, v43
	v_exp_f32_e32 v44, v44
	v_exp_f32_e32 v45, v45
	v_exp_f32_e32 v34, v34
	v_exp_f32_e32 v35, v35
	v_exp_f32_e32 v36, v36
	v_exp_f32_e32 v37, v37
	v_mul_f32_e32 v58, v57, v57
	v_add_f32_e32 v42, 1.0, v42
	v_add_f32_e32 v43, 1.0, v43
	v_add_f32_e32 v44, 1.0, v44
	v_add_f32_e32 v45, 1.0, v45
	v_add_f32_e32 v51, 1.0, v34
	v_add_f32_e32 v56, 1.0, v35
	v_add_f32_e32 v57, 1.0, v36
	v_add_f32_e32 v59, 1.0, v37
	v_rcp_f32_e32 v34, v42
	v_rcp_f32_e32 v35, v43
	v_rcp_f32_e32 v36, v44
	v_rcp_f32_e32 v37, v45
	v_rcp_f32_e32 v42, v51
	v_rcp_f32_e32 v43, v56
	v_rcp_f32_e32 v44, v57
	v_rcp_f32_e32 v45, v59
	v_mad_i64_i32 v[52:53], s[48:49], v66, s68, v[122:123]
	v_pk_mul_f32 v[34:35], v[58:59], v[34:35] op_sel_hi:[0,1]
	v_pk_mul_f32 v[36:37], v[58:59], v[36:37] op_sel_hi:[0,1]
	v_pk_mul_f32 v[42:43], v[58:59], v[42:43] op_sel_hi:[0,1]
	v_pk_mul_f32 v[44:45], v[58:59], v[44:45] op_sel_hi:[0,1]
	v_lshl_add_u64 v[52:53], v[52:53], 0, s[46:47]
	v_pk_mul_f32 v[36:37], v[48:49], v[36:37]
	v_pk_mul_f32 v[34:35], v[46:47], v[34:35]
	v_pk_mul_f32 v[40:41], v[40:41], v[44:45]
	v_pk_mul_f32 v[38:39], v[38:39], v[42:43]
	v_lshl_add_u64 v[52:53], v[52:53], 0, v[138:139]
	v_cvt_pk_bf16_f32 v34, v34, v35
	v_cvt_pk_bf16_f32 v35, v36, v37
	v_cvt_pk_bf16_f32 v36, v38, v39
	v_cvt_pk_bf16_f32 v37, v40, v41
	global_store_dwordx4 v[52:53], v[34:37], off
	v_fmamk_f32 v38, v237, 0x3a800000, v158
	v_rsq_f32_e32 v41, v38
	v_add_u32_e32 v34, 0xb0, v148
	v_mul_f32_e32 v40, 0xbfb8aa3b, v41
	v_pk_mul_f32 v[28:29], v[28:29], v[40:41] op_sel_hi:[1,0]
	v_pk_mul_f32 v[26:27], v[26:27], v[40:41] op_sel_hi:[1,0]
	v_pk_mul_f32 v[20:21], v[20:21], v[40:41] op_sel_hi:[1,0]
	v_pk_mul_f32 v[18:19], v[18:19], v[40:41] op_sel_hi:[1,0]
	v_exp_f32_e32 v26, v26
	v_exp_f32_e32 v27, v27
	v_exp_f32_e32 v28, v28
	v_exp_f32_e32 v29, v29
	v_exp_f32_e32 v18, v18
	v_exp_f32_e32 v19, v19
	v_exp_f32_e32 v20, v20
	v_exp_f32_e32 v21, v21
	v_mul_f32_e32 v42, v41, v41
	v_add_f32_e32 v26, 1.0, v26
	v_add_f32_e32 v27, 1.0, v27
	v_add_f32_e32 v28, 1.0, v28
	v_add_f32_e32 v29, 1.0, v29
	v_add_f32_e32 v35, 1.0, v18
	v_add_f32_e32 v40, 1.0, v19
	v_add_f32_e32 v41, 1.0, v20
	v_add_f32_e32 v43, 1.0, v21
	v_rcp_f32_e32 v18, v26
	v_rcp_f32_e32 v19, v27
	v_rcp_f32_e32 v20, v28
	v_rcp_f32_e32 v21, v29
	v_rcp_f32_e32 v26, v35
	v_rcp_f32_e32 v27, v40
	v_rcp_f32_e32 v28, v41
	v_rcp_f32_e32 v29, v43
	v_mad_i64_i32 v[36:37], s[48:49], v50, s68, v[122:123]
	v_pk_mul_f32 v[18:19], v[42:43], v[18:19] op_sel_hi:[0,1]
	v_pk_mul_f32 v[20:21], v[42:43], v[20:21] op_sel_hi:[0,1]
	v_pk_mul_f32 v[26:27], v[42:43], v[26:27] op_sel_hi:[0,1]
	v_pk_mul_f32 v[28:29], v[42:43], v[28:29] op_sel_hi:[0,1]
	v_lshl_add_u64 v[36:37], v[36:37], 0, s[46:47]
	v_pk_mul_f32 v[20:21], v[32:33], v[20:21]
	v_pk_mul_f32 v[18:19], v[30:31], v[18:19]
	v_pk_mul_f32 v[24:25], v[24:25], v[28:29]
	v_pk_mul_f32 v[22:23], v[22:23], v[26:27]
	v_lshl_add_u64 v[36:37], v[36:37], 0, v[138:139]
	v_cvt_pk_bf16_f32 v18, v18, v19
	v_cvt_pk_bf16_f32 v19, v20, v21
	v_cvt_pk_bf16_f32 v20, v22, v23
	v_cvt_pk_bf16_f32 v21, v24, v25
	global_store_dwordx4 v[36:37], v[18:21], off
	s_nop 0
	s_nop 0
	v_fmamk_f32 v18, v238, 0x3a800000, v158
	v_rsq_f32_e32 v21, v18
	v_mad_i64_i32 v[18:19], s[4:5], v34, s68, v[122:123]
	v_lshl_add_u64 v[18:19], v[18:19], 0, s[46:47]
	v_mul_f32_e32 v20, 0xbfb8aa3b, v21
	v_pk_mul_f32 v[12:13], v[12:13], v[20:21] op_sel_hi:[1,0]
	v_pk_mul_f32 v[10:11], v[10:11], v[20:21] op_sel_hi:[1,0]
	v_pk_mul_f32 v[8:9], v[8:9], v[20:21] op_sel_hi:[1,0]
	v_pk_mul_f32 v[6:7], v[6:7], v[20:21] op_sel_hi:[1,0]
	v_exp_f32_e32 v10, v10
	v_exp_f32_e32 v11, v11
	v_exp_f32_e32 v12, v12
	v_exp_f32_e32 v13, v13
	v_exp_f32_e32 v6, v6
	v_exp_f32_e32 v7, v7
	v_exp_f32_e32 v8, v8
	v_exp_f32_e32 v9, v9
	v_mul_f32_e32 v22, v21, v21
	v_add_f32_e32 v10, 1.0, v10
	v_add_f32_e32 v11, 1.0, v11
	v_add_f32_e32 v12, 1.0, v12
	v_add_f32_e32 v13, 1.0, v13
	v_add_f32_e32 v20, 1.0, v6
	v_add_f32_e32 v21, 1.0, v7
	v_add_f32_e32 v23, 1.0, v8
	v_add_f32_e32 v24, 1.0, v9
	v_rcp_f32_e32 v6, v10
	v_rcp_f32_e32 v7, v11
	v_rcp_f32_e32 v8, v12
	v_rcp_f32_e32 v9, v13
	v_rcp_f32_e32 v10, v20
	v_rcp_f32_e32 v11, v21
	v_rcp_f32_e32 v12, v23
	v_rcp_f32_e32 v13, v24
	v_pk_mul_f32 v[6:7], v[22:23], v[6:7] op_sel_hi:[0,1]
	v_pk_mul_f32 v[8:9], v[22:23], v[8:9] op_sel_hi:[0,1]
	v_pk_mul_f32 v[10:11], v[22:23], v[10:11] op_sel_hi:[0,1]
	v_pk_mul_f32 v[12:13], v[22:23], v[12:13] op_sel_hi:[0,1]
	v_pk_mul_f32 v[8:9], v[16:17], v[8:9]
	v_pk_mul_f32 v[6:7], v[14:15], v[6:7]
	v_pk_mul_f32 v[12:13], v[4:5], v[12:13]
	v_pk_mul_f32 v[4:5], v[2:3], v[10:11]
	v_lshl_add_u64 v[18:19], v[18:19], 0, v[138:139]
	v_cvt_pk_bf16_f32 v2, v6, v7
	v_cvt_pk_bf16_f32 v3, v8, v9
	v_cvt_pk_bf16_f32 v4, v4, v5
	v_cvt_pk_bf16_f32 v5, v12, v13
	s_mov_b64 s[4:5], -1
	global_store_dwordx4 v[18:19], v[2:5], off
	s_cbranch_vccnz .LBB0_836
	s_andn2_b64 vcc, exec, s[8:9]
	s_cbranch_vccnz .LBB0_835
	s_barrier
	s_branch .LBB0_835

.LBB0_1133:
	v_pk_mul_f32 v[128:129], v[120:121], v[128:129]
	v_pk_mul_f32 v[126:127], v[118:119], v[126:127]
	v_pk_mul_f32 v[124:125], v[116:117], v[124:125]
	v_pk_mul_f32 v[160:161], v[114:115], v[122:123]
	v_add_u32_e32 v162, s25, v152
	s_lshl_b32 s46, s47, 7
	v_mov_b64_e32 v[122:123], s[10:11]
	s_ashr_i32 s47, s46, 31
	v_mad_i64_i32 v[164:165], s[48:49], v148, s68, v[122:123]
	s_lshl_b64 s[46:47], s[46:47], 1
	v_lshl_add_u64 v[164:165], v[164:165], 0, s[46:47]
	v_lshl_add_u64 v[164:165], v[164:165], 0, v[138:139]
	v_pk_mul_f32 v[112:113], v[108:109], v[112:113]
	v_pk_mul_f32 v[110:111], v[106:107], v[110:111]
	v_pk_mul_f32 v[104:105], v[100:101], v[104:105]
	v_pk_mul_f32 v[102:103], v[98:99], v[102:103]
	v_pk_mul_f32 v[96:97], v[92:93], v[96:97]
	v_pk_mul_f32 v[94:95], v[90:91], v[94:95]
	v_pk_mul_f32 v[88:89], v[84:85], v[88:89]
	v_pk_mul_f32 v[86:87], v[82:83], v[86:87]
	v_pk_mul_f32 v[80:81], v[76:77], v[80:81]
	v_pk_mul_f32 v[78:79], v[74:75], v[78:79]
	v_pk_mul_f32 v[72:73], v[68:69], v[72:73]
	v_pk_mul_f32 v[70:71], v[66:67], v[70:71]
	v_pk_mul_f32 v[64:65], v[60:61], v[64:65]
	v_pk_mul_f32 v[62:63], v[58:59], v[62:63]
	v_pk_mul_f32 v[56:57], v[52:53], v[56:57]
	v_pk_mul_f32 v[54:55], v[50:51], v[54:55]
	v_pk_mul_f32 v[48:49], v[44:45], v[48:49]
	v_pk_mul_f32 v[46:47], v[42:43], v[46:47]
	v_pk_mul_f32 v[40:41], v[36:37], v[40:41]
	v_pk_mul_f32 v[38:39], v[34:35], v[38:39]
	v_pk_mul_f32 v[32:33], v[28:29], v[32:33]
	v_pk_mul_f32 v[30:31], v[26:27], v[30:31]
	v_pk_mul_f32 v[24:25], v[20:21], v[24:25]
	v_pk_mul_f32 v[22:23], v[18:19], v[22:23]
	v_pk_mul_f32 v[16:17], v[12:13], v[16:17]
	v_pk_mul_f32 v[14:15], v[10:11], v[14:15]
	v_pk_mul_f32 v[4:5], v[8:9], v[4:5]
	v_pk_mul_f32 v[2:3], v[6:7], v[2:3]
	s_andn2_b64 vcc, exec, s[4:5]
	s_waitcnt vmcnt(0)
	v_fmamk_f32 v149, v149, 0x3a800000, v158
	v_rsq_f32_e32 v149, v149
	s_nop 0
	v_mul_f32_e32 v168, 0xbfb8aa3b, v149
	v_pk_mul_f32 v[120:121], v[120:121], v[168:169] op_sel_hi:[1,0]
	v_pk_mul_f32 v[118:119], v[118:119], v[168:169] op_sel_hi:[1,0]
	v_pk_mul_f32 v[116:117], v[116:117], v[168:169] op_sel_hi:[1,0]
	v_pk_mul_f32 v[114:115], v[114:115], v[168:169] op_sel_hi:[1,0]
	v_exp_f32_e32 v118, v118
	v_exp_f32_e32 v119, v119
	v_exp_f32_e32 v120, v120
	v_exp_f32_e32 v121, v121
	v_exp_f32_e32 v114, v114
	v_exp_f32_e32 v115, v115
	v_exp_f32_e32 v116, v116
	v_exp_f32_e32 v117, v117
	v_mul_f32_e32 v170, v149, v149
	v_add_f32_e32 v118, 1.0, v118
	v_add_f32_e32 v119, 1.0, v119
	v_add_f32_e32 v120, 1.0, v120
	v_add_f32_e32 v121, 1.0, v121
	v_add_f32_e32 v149, 1.0, v114
	v_add_f32_e32 v159, 1.0, v115
	v_add_f32_e32 v163, 1.0, v116
	v_add_f32_e32 v168, 1.0, v117
	v_rcp_f32_e32 v114, v118
	v_rcp_f32_e32 v115, v119
	v_rcp_f32_e32 v116, v120
	v_rcp_f32_e32 v117, v121
	v_rcp_f32_e32 v118, v149
	v_rcp_f32_e32 v119, v159
	v_rcp_f32_e32 v120, v163
	v_rcp_f32_e32 v121, v168
	v_pk_mul_f32 v[114:115], v[170:171], v[114:115] op_sel_hi:[0,1]
	v_pk_mul_f32 v[116:117], v[170:171], v[116:117] op_sel_hi:[0,1]
	v_pk_mul_f32 v[118:119], v[170:171], v[118:119] op_sel_hi:[0,1]
	v_pk_mul_f32 v[120:121], v[170:171], v[120:121] op_sel_hi:[0,1]
	v_pk_mul_f32 v[116:117], v[128:129], v[116:117]
	v_pk_mul_f32 v[114:115], v[126:127], v[114:115]
	v_pk_mul_f32 v[120:121], v[124:125], v[120:121]
	v_pk_mul_f32 v[118:119], v[160:161], v[118:119]
	v_cvt_pk_bf16_f32 v114, v114, v115
	v_cvt_pk_bf16_f32 v115, v116, v117
	v_cvt_pk_bf16_f32 v116, v118, v119
	v_cvt_pk_bf16_f32 v117, v120, v121
	global_store_dwordx4 v[164:165], v[114:117], off
	v_fmamk_f32 v118, v232, 0x3a800000, v158
	v_rsq_f32_e32 v121, v118
	v_add_u32_e32 v114, s25, v153
	v_mul_f32_e32 v120, 0xbfb8aa3b, v121
	v_pk_mul_f32 v[108:109], v[108:109], v[120:121] op_sel_hi:[1,0]
	v_pk_mul_f32 v[106:107], v[106:107], v[120:121] op_sel_hi:[1,0]
	v_pk_mul_f32 v[100:101], v[100:101], v[120:121] op_sel_hi:[1,0]
	v_pk_mul_f32 v[98:99], v[98:99], v[120:121] op_sel_hi:[1,0]
	v_exp_f32_e32 v106, v106
	v_exp_f32_e32 v107, v107
	v_exp_f32_e32 v108, v108
	v_exp_f32_e32 v109, v109
	v_exp_f32_e32 v98, v98
	v_exp_f32_e32 v99, v99
	v_exp_f32_e32 v100, v100
	v_exp_f32_e32 v101, v101
	v_mul_f32_e32 v124, v121, v121
	v_add_f32_e32 v106, 1.0, v106
	v_add_f32_e32 v107, 1.0, v107
	v_add_f32_e32 v108, 1.0, v108
	v_add_f32_e32 v109, 1.0, v109
	v_add_f32_e32 v115, 1.0, v98
	v_add_f32_e32 v120, 1.0, v99
	v_add_f32_e32 v121, 1.0, v100
	v_add_f32_e32 v125, 1.0, v101
	v_rcp_f32_e32 v98, v106
	v_rcp_f32_e32 v99, v107
	v_rcp_f32_e32 v100, v108
	v_rcp_f32_e32 v101, v109
	v_rcp_f32_e32 v106, v115
	v_rcp_f32_e32 v107, v120
	v_rcp_f32_e32 v108, v121
	v_rcp_f32_e32 v109, v125
	v_mad_i64_i32 v[116:117], s[48:49], v162, s68, v[122:123]
	v_pk_mul_f32 v[98:99], v[124:125], v[98:99] op_sel_hi:[0,1]
	v_pk_mul_f32 v[100:101], v[124:125], v[100:101] op_sel_hi:[0,1]
	v_pk_mul_f32 v[106:107], v[124:125], v[106:107] op_sel_hi:[0,1]
	v_pk_mul_f32 v[108:109], v[124:125], v[108:109] op_sel_hi:[0,1]
	v_lshl_add_u64 v[116:117], v[116:117], 0, s[46:47]
	v_pk_mul_f32 v[100:101], v[112:113], v[100:101]
	v_pk_mul_f32 v[98:99], v[110:111], v[98:99]
	v_pk_mul_f32 v[104:105], v[104:105], v[108:109]
	v_pk_mul_f32 v[102:103], v[102:103], v[106:107]
	v_lshl_add_u64 v[116:117], v[116:117], 0, v[138:139]
	v_cvt_pk_bf16_f32 v98, v98, v99
	v_cvt_pk_bf16_f32 v99, v100, v101
	v_cvt_pk_bf16_f32 v100, v102, v103
	v_cvt_pk_bf16_f32 v101, v104, v105
	global_store_dwordx4 v[116:117], v[98:101], off
	v_fmamk_f32 v102, v233, 0x3a800000, v158
	v_rsq_f32_e32 v105, v102
	v_add_u32_e32 v98, s25, v154
	v_mul_f32_e32 v104, 0xbfb8aa3b, v105
	v_pk_mul_f32 v[92:93], v[92:93], v[104:105] op_sel_hi:[1,0]
	v_pk_mul_f32 v[90:91], v[90:91], v[104:105] op_sel_hi:[1,0]
	v_pk_mul_f32 v[84:85], v[84:85], v[104:105] op_sel_hi:[1,0]
	v_pk_mul_f32 v[82:83], v[82:83], v[104:105] op_sel_hi:[1,0]
	v_exp_f32_e32 v90, v90
	v_exp_f32_e32 v91, v91
	v_exp_f32_e32 v92, v92
	v_exp_f32_e32 v93, v93
	v_exp_f32_e32 v82, v82
	v_exp_f32_e32 v83, v83
	v_exp_f32_e32 v84, v84
	v_exp_f32_e32 v85, v85
	v_mul_f32_e32 v106, v105, v105
	v_add_f32_e32 v90, 1.0, v90
	v_add_f32_e32 v91, 1.0, v91
	v_add_f32_e32 v92, 1.0, v92
	v_add_f32_e32 v93, 1.0, v93
	v_add_f32_e32 v99, 1.0, v82
	v_add_f32_e32 v104, 1.0, v83
	v_add_f32_e32 v105, 1.0, v84
	v_add_f32_e32 v107, 1.0, v85
	v_rcp_f32_e32 v82, v90
	v_rcp_f32_e32 v83, v91
	v_rcp_f32_e32 v84, v92
	v_rcp_f32_e32 v85, v93
	v_rcp_f32_e32 v90, v99
	v_rcp_f32_e32 v91, v104
	v_rcp_f32_e32 v92, v105
	v_rcp_f32_e32 v93, v107
	v_mad_i64_i32 v[100:101], s[48:49], v114, s68, v[122:123]
	v_pk_mul_f32 v[82:83], v[106:107], v[82:83] op_sel_hi:[0,1]
	v_pk_mul_f32 v[84:85], v[106:107], v[84:85] op_sel_hi:[0,1]
	v_pk_mul_f32 v[90:91], v[106:107], v[90:91] op_sel_hi:[0,1]
	v_pk_mul_f32 v[92:93], v[106:107], v[92:93] op_sel_hi:[0,1]
	v_lshl_add_u64 v[100:101], v[100:101], 0, s[46:47]
	v_pk_mul_f32 v[84:85], v[96:97], v[84:85]
	v_pk_mul_f32 v[82:83], v[94:95], v[82:83]
	v_pk_mul_f32 v[88:89], v[88:89], v[92:93]
	v_pk_mul_f32 v[86:87], v[86:87], v[90:91]
	v_lshl_add_u64 v[100:101], v[100:101], 0, v[138:139]
	v_cvt_pk_bf16_f32 v82, v82, v83
	v_cvt_pk_bf16_f32 v83, v84, v85
	v_cvt_pk_bf16_f32 v84, v86, v87
	v_cvt_pk_bf16_f32 v85, v88, v89
	global_store_dwordx4 v[100:101], v[82:85], off
	s_nop 0
	s_nop 0
	v_add_u32_e32 v84, 0x80, v148
	v_mad_i64_i32 v[82:83], s[48:49], v98, s68, v[122:123]
	v_lshl_add_u64 v[82:83], v[82:83], 0, s[46:47]
	v_lshl_add_u64 v[82:83], v[82:83], 0, v[138:139]
	v_fmamk_f32 v85, v234, 0x3a800000, v158
	v_rsq_f32_e32 v89, v85
	s_nop 0
	v_mul_f32_e32 v88, 0xbfb8aa3b, v89
	v_pk_mul_f32 v[76:77], v[76:77], v[88:89] op_sel_hi:[1,0]
	v_pk_mul_f32 v[74:75], v[74:75], v[88:89] op_sel_hi:[1,0]
	v_pk_mul_f32 v[68:69], v[68:69], v[88:89] op_sel_hi:[1,0]
	v_pk_mul_f32 v[66:67], v[66:67], v[88:89] op_sel_hi:[1,0]
	v_exp_f32_e32 v74, v74
	v_exp_f32_e32 v75, v75
	v_exp_f32_e32 v76, v76
	v_exp_f32_e32 v77, v77
	v_exp_f32_e32 v66, v66
	v_exp_f32_e32 v67, v67
	v_exp_f32_e32 v68, v68
	v_exp_f32_e32 v69, v69
	v_mul_f32_e32 v90, v89, v89
	v_add_f32_e32 v74, 1.0, v74
	v_add_f32_e32 v75, 1.0, v75
	v_add_f32_e32 v76, 1.0, v76
	v_add_f32_e32 v77, 1.0, v77
	v_add_f32_e32 v85, 1.0, v66
	v_add_f32_e32 v88, 1.0, v67
	v_add_f32_e32 v89, 1.0, v68
	v_add_f32_e32 v91, 1.0, v69
	v_rcp_f32_e32 v66, v74
	v_rcp_f32_e32 v67, v75
	v_rcp_f32_e32 v68, v76
	v_rcp_f32_e32 v69, v77
	v_rcp_f32_e32 v74, v85
	v_rcp_f32_e32 v75, v88
	v_rcp_f32_e32 v76, v89
	v_rcp_f32_e32 v77, v91
	v_pk_mul_f32 v[66:67], v[90:91], v[66:67] op_sel_hi:[0,1]
	v_pk_mul_f32 v[68:69], v[90:91], v[68:69] op_sel_hi:[0,1]
	v_pk_mul_f32 v[74:75], v[90:91], v[74:75] op_sel_hi:[0,1]
	v_pk_mul_f32 v[76:77], v[90:91], v[76:77] op_sel_hi:[0,1]
	v_pk_mul_f32 v[68:69], v[80:81], v[68:69]
	v_pk_mul_f32 v[66:67], v[78:79], v[66:67]
	v_pk_mul_f32 v[72:73], v[72:73], v[76:77]
	v_pk_mul_f32 v[70:71], v[70:71], v[74:75]
	v_cvt_pk_bf16_f32 v66, v66, v67
	v_cvt_pk_bf16_f32 v67, v68, v69
	v_cvt_pk_bf16_f32 v68, v70, v71
	v_cvt_pk_bf16_f32 v69, v72, v73
	global_store_dwordx4 v[82:83], v[66:69], off
	v_fmamk_f32 v70, v235, 0x3a800000, v158
	v_rsq_f32_e32 v73, v70
	v_add_u32_e32 v66, 0x90, v148
	v_mul_f32_e32 v72, 0xbfb8aa3b, v73
	v_pk_mul_f32 v[60:61], v[60:61], v[72:73] op_sel_hi:[1,0]
	v_pk_mul_f32 v[58:59], v[58:59], v[72:73] op_sel_hi:[1,0]
	v_pk_mul_f32 v[52:53], v[52:53], v[72:73] op_sel_hi:[1,0]
	v_pk_mul_f32 v[50:51], v[50:51], v[72:73] op_sel_hi:[1,0]
	v_exp_f32_e32 v58, v58
	v_exp_f32_e32 v59, v59
	v_exp_f32_e32 v60, v60
	v_exp_f32_e32 v61, v61
	v_exp_f32_e32 v50, v50
	v_exp_f32_e32 v51, v51
	v_exp_f32_e32 v52, v52
	v_exp_f32_e32 v53, v53
	v_mul_f32_e32 v74, v73, v73
	v_add_f32_e32 v58, 1.0, v58
	v_add_f32_e32 v59, 1.0, v59
	v_add_f32_e32 v60, 1.0, v60
	v_add_f32_e32 v61, 1.0, v61
	v_add_f32_e32 v67, 1.0, v50
	v_add_f32_e32 v72, 1.0, v51
	v_add_f32_e32 v73, 1.0, v52
	v_add_f32_e32 v75, 1.0, v53
	v_rcp_f32_e32 v50, v58
	v_rcp_f32_e32 v51, v59
	v_rcp_f32_e32 v52, v60
	v_rcp_f32_e32 v53, v61
	v_rcp_f32_e32 v58, v67
	v_rcp_f32_e32 v59, v72
	v_rcp_f32_e32 v60, v73
	v_rcp_f32_e32 v61, v75
	v_mad_i64_i32 v[68:69], s[48:49], v84, s68, v[122:123]
	v_pk_mul_f32 v[50:51], v[74:75], v[50:51] op_sel_hi:[0,1]
	v_pk_mul_f32 v[52:53], v[74:75], v[52:53] op_sel_hi:[0,1]
	v_pk_mul_f32 v[58:59], v[74:75], v[58:59] op_sel_hi:[0,1]
	v_pk_mul_f32 v[60:61], v[74:75], v[60:61] op_sel_hi:[0,1]
	v_lshl_add_u64 v[68:69], v[68:69], 0, s[46:47]
	v_pk_mul_f32 v[52:53], v[64:65], v[52:53]
	v_pk_mul_f32 v[50:51], v[62:63], v[50:51]
	v_pk_mul_f32 v[56:57], v[56:57], v[60:61]
	v_pk_mul_f32 v[54:55], v[54:55], v[58:59]
	v_lshl_add_u64 v[68:69], v[68:69], 0, v[138:139]
	v_cvt_pk_bf16_f32 v50, v50, v51
	v_cvt_pk_bf16_f32 v51, v52, v53
	v_cvt_pk_bf16_f32 v52, v54, v55
	v_cvt_pk_bf16_f32 v53, v56, v57
	global_store_dwordx4 v[68:69], v[50:53], off
	v_fmamk_f32 v54, v236, 0x3a800000, v158
	v_rsq_f32_e32 v57, v54
	v_add_u32_e32 v50, 0xa0, v148
	v_mul_f32_e32 v56, 0xbfb8aa3b, v57
	v_pk_mul_f32 v[44:45], v[44:45], v[56:57] op_sel_hi:[1,0]
	v_pk_mul_f32 v[42:43], v[42:43], v[56:57] op_sel_hi:[1,0]
	v_pk_mul_f32 v[36:37], v[36:37], v[56:57] op_sel_hi:[1,0]
	v_pk_mul_f32 v[34:35], v[34:35], v[56:57] op_sel_hi:[1,0]
	v_exp_f32_e32 v42, v42
	v_exp_f32_e32 v43, v43
	v_exp_f32_e32 v44, v44
	v_exp_f32_e32 v45, v45
	v_exp_f32_e32 v34, v34
	v_exp_f32_e32 v35, v35
	v_exp_f32_e32 v36, v36
	v_exp_f32_e32 v37, v37
	v_mul_f32_e32 v58, v57, v57
	v_add_f32_e32 v42, 1.0, v42
	v_add_f32_e32 v43, 1.0, v43
	v_add_f32_e32 v44, 1.0, v44
	v_add_f32_e32 v45, 1.0, v45
	v_add_f32_e32 v51, 1.0, v34
	v_add_f32_e32 v56, 1.0, v35
	v_add_f32_e32 v57, 1.0, v36
	v_add_f32_e32 v59, 1.0, v37
	v_rcp_f32_e32 v34, v42
	v_rcp_f32_e32 v35, v43
	v_rcp_f32_e32 v36, v44
	v_rcp_f32_e32 v37, v45
	v_rcp_f32_e32 v42, v51
	v_rcp_f32_e32 v43, v56
	v_rcp_f32_e32 v44, v57
	v_rcp_f32_e32 v45, v59
	v_mad_i64_i32 v[52:53], s[48:49], v66, s68, v[122:123]
	v_pk_mul_f32 v[34:35], v[58:59], v[34:35] op_sel_hi:[0,1]
	v_pk_mul_f32 v[36:37], v[58:59], v[36:37] op_sel_hi:[0,1]
	v_pk_mul_f32 v[42:43], v[58:59], v[42:43] op_sel_hi:[0,1]
	v_pk_mul_f32 v[44:45], v[58:59], v[44:45] op_sel_hi:[0,1]
	v_lshl_add_u64 v[52:53], v[52:53], 0, s[46:47]
	v_pk_mul_f32 v[36:37], v[48:49], v[36:37]
	v_pk_mul_f32 v[34:35], v[46:47], v[34:35]
	v_pk_mul_f32 v[40:41], v[40:41], v[44:45]
	v_pk_mul_f32 v[38:39], v[38:39], v[42:43]
	v_lshl_add_u64 v[52:53], v[52:53], 0, v[138:139]
	v_cvt_pk_bf16_f32 v34, v34, v35
	v_cvt_pk_bf16_f32 v35, v36, v37
	v_cvt_pk_bf16_f32 v36, v38, v39
	v_cvt_pk_bf16_f32 v37, v40, v41
	global_store_dwordx4 v[52:53], v[34:37], off
	v_fmamk_f32 v38, v237, 0x3a800000, v158
	v_rsq_f32_e32 v41, v38
	v_add_u32_e32 v34, 0xb0, v148
	v_mul_f32_e32 v40, 0xbfb8aa3b, v41
	v_pk_mul_f32 v[28:29], v[28:29], v[40:41] op_sel_hi:[1,0]
	v_pk_mul_f32 v[26:27], v[26:27], v[40:41] op_sel_hi:[1,0]
	v_pk_mul_f32 v[20:21], v[20:21], v[40:41] op_sel_hi:[1,0]
	v_pk_mul_f32 v[18:19], v[18:19], v[40:41] op_sel_hi:[1,0]
	v_exp_f32_e32 v26, v26
	v_exp_f32_e32 v27, v27
	v_exp_f32_e32 v28, v28
	v_exp_f32_e32 v29, v29
	v_exp_f32_e32 v18, v18
	v_exp_f32_e32 v19, v19
	v_exp_f32_e32 v20, v20
	v_exp_f32_e32 v21, v21
	v_mul_f32_e32 v42, v41, v41
	v_add_f32_e32 v26, 1.0, v26
	v_add_f32_e32 v27, 1.0, v27
	v_add_f32_e32 v28, 1.0, v28
	v_add_f32_e32 v29, 1.0, v29
	v_add_f32_e32 v35, 1.0, v18
	v_add_f32_e32 v40, 1.0, v19
	v_add_f32_e32 v41, 1.0, v20
	v_add_f32_e32 v43, 1.0, v21
	v_rcp_f32_e32 v18, v26
	v_rcp_f32_e32 v19, v27
	v_rcp_f32_e32 v20, v28
	v_rcp_f32_e32 v21, v29
	v_rcp_f32_e32 v26, v35
	v_rcp_f32_e32 v27, v40
	v_rcp_f32_e32 v28, v41
	v_rcp_f32_e32 v29, v43
	v_mad_i64_i32 v[36:37], s[48:49], v50, s68, v[122:123]
	v_pk_mul_f32 v[18:19], v[42:43], v[18:19] op_sel_hi:[0,1]
	v_pk_mul_f32 v[20:21], v[42:43], v[20:21] op_sel_hi:[0,1]
	v_pk_mul_f32 v[26:27], v[42:43], v[26:27] op_sel_hi:[0,1]
	v_pk_mul_f32 v[28:29], v[42:43], v[28:29] op_sel_hi:[0,1]
	v_lshl_add_u64 v[36:37], v[36:37], 0, s[46:47]
	v_pk_mul_f32 v[20:21], v[32:33], v[20:21]
	v_pk_mul_f32 v[18:19], v[30:31], v[18:19]
	v_pk_mul_f32 v[24:25], v[24:25], v[28:29]
	v_pk_mul_f32 v[22:23], v[22:23], v[26:27]
	v_lshl_add_u64 v[36:37], v[36:37], 0, v[138:139]
	v_cvt_pk_bf16_f32 v18, v18, v19
	v_cvt_pk_bf16_f32 v19, v20, v21
	v_cvt_pk_bf16_f32 v20, v22, v23
	v_cvt_pk_bf16_f32 v21, v24, v25
	global_store_dwordx4 v[36:37], v[18:21], off
	s_nop 0
	s_nop 0
	v_fmamk_f32 v18, v238, 0x3a800000, v158
	v_rsq_f32_e32 v21, v18
	v_mad_i64_i32 v[18:19], s[4:5], v34, s68, v[122:123]
	v_lshl_add_u64 v[18:19], v[18:19], 0, s[46:47]
	v_mul_f32_e32 v20, 0xbfb8aa3b, v21
	v_pk_mul_f32 v[12:13], v[12:13], v[20:21] op_sel_hi:[1,0]
	v_pk_mul_f32 v[10:11], v[10:11], v[20:21] op_sel_hi:[1,0]
	v_pk_mul_f32 v[8:9], v[8:9], v[20:21] op_sel_hi:[1,0]
	v_pk_mul_f32 v[6:7], v[6:7], v[20:21] op_sel_hi:[1,0]
	v_exp_f32_e32 v10, v10
	v_exp_f32_e32 v11, v11
	v_exp_f32_e32 v12, v12
	v_exp_f32_e32 v13, v13
	v_exp_f32_e32 v6, v6
	v_exp_f32_e32 v7, v7
	v_exp_f32_e32 v8, v8
	v_exp_f32_e32 v9, v9
	v_mul_f32_e32 v22, v21, v21
	v_add_f32_e32 v10, 1.0, v10
	v_add_f32_e32 v11, 1.0, v11
	v_add_f32_e32 v12, 1.0, v12
	v_add_f32_e32 v13, 1.0, v13
	v_add_f32_e32 v20, 1.0, v6
	v_add_f32_e32 v21, 1.0, v7
	v_add_f32_e32 v23, 1.0, v8
	v_add_f32_e32 v24, 1.0, v9
	v_rcp_f32_e32 v6, v10
	v_rcp_f32_e32 v7, v11
	v_rcp_f32_e32 v8, v12
	v_rcp_f32_e32 v9, v13
	v_rcp_f32_e32 v10, v20
	v_rcp_f32_e32 v11, v21
	v_rcp_f32_e32 v12, v23
	v_rcp_f32_e32 v13, v24
	v_pk_mul_f32 v[6:7], v[22:23], v[6:7] op_sel_hi:[0,1]
	v_pk_mul_f32 v[8:9], v[22:23], v[8:9] op_sel_hi:[0,1]
	v_pk_mul_f32 v[10:11], v[22:23], v[10:11] op_sel_hi:[0,1]
	v_pk_mul_f32 v[12:13], v[22:23], v[12:13] op_sel_hi:[0,1]
	v_pk_mul_f32 v[8:9], v[16:17], v[8:9]
	v_pk_mul_f32 v[6:7], v[14:15], v[6:7]
	v_pk_mul_f32 v[12:13], v[4:5], v[12:13]
	v_pk_mul_f32 v[4:5], v[2:3], v[10:11]
	v_lshl_add_u64 v[18:19], v[18:19], 0, v[138:139]
	v_cvt_pk_bf16_f32 v2, v6, v7
	v_cvt_pk_bf16_f32 v3, v8, v9
	v_cvt_pk_bf16_f32 v4, v4, v5
	v_cvt_pk_bf16_f32 v5, v12, v13
	s_mov_b64 s[4:5], -1
	global_store_dwordx4 v[18:19], v[2:5], off
	s_cbranch_vccnz .LBB0_1126
	s_andn2_b64 vcc, exec, s[6:7]
	s_cbranch_vccnz .LBB0_1125
	s_barrier
	s_branch .LBB0_1125
